# FoX key tiles visited newest-first; a tile whose logits are all below running max - 152 (softmax weights exactly 0 in f32) skips exp/PV (exact: contributes 0)
# speedup vs baseline: 1.0108x; 1.0108x over previous
.LBB0_626:
	v_mov_b32_e32 v18, v255
	s_and_b32 s50, s88, 7
	s_ashr_i32 s0, s88, 7
	s_xor_b32 s51, s50, 15
	v_readfirstlane_b32 s5, v18
	s_ashr_i32 s1, s0, 31
	s_ashr_i32 s33, s5, 1
	s_lshl_b64 s[22:23], s[0:1], 12
	s_lshl_b32 s60, s51, 8
	s_andn2_b32 s33, s33, 31
	s_bfe_u32 s4, s88, 0x40003
	s_lshl_b64 s[6:7], s[0:1], 26
	s_or_b32 s1, s22, s60
	s_ashr_i32 s16, s33, 31
	s_add_u32 s24, s1, s33
	v_and_b32_e32 v30, 31, v18
	s_addc_u32 s25, s23, s16
	v_or_b32_e32 v2, s24, v30
	v_mov_b32_e32 v3, s25
	v_lshlrev_b64 v[2:3], 14, v[2:3]
	v_bfe_u32 v31, v18, 5, 1
	v_lshl_add_u64 v[2:3], s[12:13], 0, v[2:3]
	s_lshl_b32 s16, s4, 8
	v_lshl_add_u64 v[2:3], v[2:3], 0, s[16:17]
	v_lshlrev_b32_e32 v0, 4, v31
	v_ashrrev_i32_e32 v19, 31, v18
	v_lshl_add_u64 v[2:3], v[2:3], 0, v[0:1]
	v_lshrrev_b32_e32 v0, 28, v19
	s_add_u32 s1, s12, s6
	v_add_u32_e32 v0, v18, v0
	s_addc_u32 s6, s13, s7
	v_ashrrev_i32_e32 v146, 4, v0
	v_and_b32_e32 v0, -16, v0
	s_add_u32 s20, s1, s16
	v_sub_u32_e32 v0, v18, v0
	v_ashrrev_i32_e32 v147, 31, v146
	global_load_dwordx4 v[98:101], v[2:3], off
	global_load_dwordx4 v[102:105], v[2:3], off offset:32
	global_load_dwordx4 v[106:109], v[2:3], off offset:64
	global_load_dwordx4 v[110:113], v[2:3], off offset:96
	global_load_dwordx4 v[114:117], v[2:3], off offset:128
	global_load_dwordx4 v[118:121], v[2:3], off offset:160
	global_load_dwordx4 v[122:125], v[2:3], off offset:192
	global_load_dwordx4 v[126:129], v[2:3], off offset:224
	s_addc_u32 s21, s6, 0
	v_lshlrev_b64 v[2:3], 14, v[146:147]
	v_lshlrev_b32_e32 v20, 3, v0
	s_lshl_b32 s84, s51, 22
	s_add_u32 s84, s84, 0x300000
	s_add_u32 s84, s20, s84
	s_addc_u32 s85, s21, 0
	s_sub_u32 s86, s84, 0x200000
	s_subb_u32 s87, s85, 0
	v_lshl_add_u64 v[2:3], s[84:85], 0, v[2:3]
	v_ashrrev_i32_e32 v21, 31, v20
	v_lshl_add_u64 v[2:3], v[20:21], 1, v[2:3]
	v_add_co_u32_e32 v2, vcc, s43, v2
	s_cmp_gt_u32 s5, 63
	s_nop 0
	v_addc_co_u32_e32 v3, vcc, 0, v3, vcc
	global_load_dwordx4 v[14:17], v[2:3], off offset:-4096
	global_load_dwordx4 v[10:13], v[2:3], off
	v_add_u32_e32 v2, 0x200, v18
	v_ashrrev_i32_e32 v3, 31, v2
	v_lshrrev_b32_e32 v3, 28, v3
	v_add_u32_e32 v3, v2, v3
	v_ashrrev_i32_e32 v148, 4, v3
	v_and_b32_e32 v3, -16, v3
	v_sub_u32_e32 v32, v2, v3
	v_ashrrev_i32_e32 v149, 31, v148
	v_lshlrev_b64 v[2:3], 14, v[148:149]
	v_lshlrev_b32_e32 v22, 3, v32
	v_lshl_add_u64 v[2:3], s[84:85], 0, v[2:3]
	v_ashrrev_i32_e32 v23, 31, v22
	v_lshl_add_u64 v[2:3], v[22:23], 1, v[2:3]
	v_add_co_u32_e32 v4, vcc, 0x1000, v2
	v_and_b32_e32 v156, 63, v18
	s_nop 0
	v_addc_co_u32_e32 v5, vcc, 0, v3, vcc
	v_add_co_u32_e32 v6, vcc, 0x2000, v2
	s_nop 1
	v_addc_co_u32_e32 v7, vcc, 0, v3, vcc
	global_load_dwordx4 v[2:5], v[4:5], off
	s_nop 0
	global_load_dwordx4 v[6:9], v[6:7], off
	s_cbranch_scc1 .LBB0_628
	s_lshl_b32 s1, s0, 10
	v_lshl_or_b32 v24, v156, 4, s1
	v_or_b32_e32 v24, s4, v24
	v_ashrrev_i32_e32 v25, 31, v24
	v_lshl_add_u64 v[24:25], v[24:25], 2, s[14:15]
	global_load_dword v24, v[24:25], off
	v_and_b32_e32 v25, 64, v154
	v_add_u32_e32 v26, -1, v154
	v_cmp_lt_i32_e32 vcc, v26, v25
	v_add_u32_e32 v27, -2, v154
	v_add_u32_e32 v28, -4, v154
	v_cndmask_b32_e32 v26, v26, v154, vcc
	v_lshlrev_b32_e32 v26, 2, v26
	v_cmp_lt_i32_e32 vcc, v27, v25
	s_waitcnt vmcnt(0)
	ds_bpermute_b32 v26, v26, v24
	v_cndmask_b32_e32 v27, v27, v154, vcc
	v_cmp_eq_u32_e32 vcc, 0, v156
	v_lshlrev_b32_e32 v27, 2, v27
	s_waitcnt lgkmcnt(0)
	v_add_f32_e32 v26, v24, v26
	v_cndmask_b32_e32 v26, v26, v24, vcc
	ds_bpermute_b32 v27, v27, v26
	v_cmp_lt_i32_e32 vcc, v28, v25
	s_waitcnt lgkmcnt(0)
	v_add_f32_e32 v27, v26, v27
	v_cndmask_b32_e32 v28, v28, v154, vcc
	v_cmp_gt_u32_e32 vcc, 2, v156
	v_lshlrev_b32_e32 v28, 2, v28
	s_nop 0
	v_cndmask_b32_e32 v26, v27, v26, vcc
	ds_bpermute_b32 v27, v28, v26
	v_add_u32_e32 v28, -8, v154
	v_cmp_lt_i32_e32 vcc, v28, v25
	s_waitcnt lgkmcnt(0)
	v_add_f32_e32 v27, v26, v27
	v_cndmask_b32_e32 v28, v28, v154, vcc
	v_cmp_gt_u32_e32 vcc, 4, v156
	v_lshlrev_b32_e32 v28, 2, v28
	s_nop 0
	v_cndmask_b32_e32 v26, v27, v26, vcc
	ds_bpermute_b32 v27, v28, v26
	v_add_u32_e32 v28, -16, v154
	v_cmp_lt_i32_e32 vcc, v28, v25
	s_waitcnt lgkmcnt(0)
	v_add_f32_e32 v27, v26, v27
	v_cndmask_b32_e32 v28, v28, v154, vcc
	v_cmp_gt_u32_e32 vcc, 8, v156
	v_lshlrev_b32_e32 v28, 2, v28
	s_nop 0
	v_cndmask_b32_e32 v26, v27, v26, vcc
	ds_bpermute_b32 v27, v28, v26
	v_subrev_u32_e32 v28, 32, v154
	v_cmp_lt_i32_e32 vcc, v28, v25
	s_waitcnt lgkmcnt(0)
	v_add_f32_e32 v27, v26, v27
	v_cndmask_b32_e32 v25, v28, v154, vcc
	v_cmp_gt_u32_e32 vcc, 16, v156
	v_lshlrev_b32_e32 v25, 2, v25
	s_nop 0
	v_cndmask_b32_e32 v26, v27, v26, vcc
	ds_bpermute_b32 v25, v25, v26
	v_cmp_gt_u32_e32 vcc, 32, v156
	v_lshl_add_u32 v27, v156, 2, 0
	s_waitcnt lgkmcnt(0)
	v_add_f32_e32 v25, v26, v25
	v_cndmask_b32_e32 v25, v25, v26, vcc
	v_sub_f32_e32 v24, v25, v24
	v_add_u32_e32 v25, 0x16800, v27
	ds_write_b32 v25, v24

.LBB0_646:
	v_mul_lo_u32 v157, v146, s45
	v_lshlrev_b32_e32 v158, 4, v0
	v_add3_u32 v0, 0, v157, v158
	s_waitcnt vmcnt(0)
	ds_write_b128 v0, v[14:17]
	v_mad_u64_u32 v[14:15], s[4:5], v146, 48, v[0:1]
	ds_write_b128 v14, v[10:13] offset:34816
	v_lshlrev_b64 v[10:11], 14, v[146:147]
	v_lshl_add_u64 v[10:11], s[86:87], 0, v[10:11]
	v_lshlrev_b64 v[12:13], 1, v[20:21]
	v_lshl_add_u64 v[10:11], v[10:11], 0, v[12:13]
	v_add_co_u32_e32 v10, vcc, s47, v10
	v_lshlrev_b64 v[14:15], 1, v[22:23]
	s_nop 0
	v_addc_co_u32_e32 v11, vcc, 0, v11, vcc
	global_load_dwordx4 v[130:133], v[10:11], off offset:-4096
	global_load_dwordx4 v[134:137], v[10:11], off
	v_lshlrev_b64 v[10:11], 14, v[148:149]
	v_lshl_add_u64 v[10:11], s[86:87], 0, v[10:11]
	v_lshl_add_u64 v[10:11], v[10:11], 0, v[14:15]
	v_add_co_u32_e32 v10, vcc, s47, v10
	v_mul_lo_u32 v160, v148, s45
	s_nop 0
	v_addc_co_u32_e32 v11, vcc, 0, v11, vcc
	global_load_dwordx4 v[138:141], v[10:11], off offset:-4096
	global_load_dwordx4 v[142:145], v[10:11], off
	v_lshlrev_b32_e32 v161, 4, v32
	v_add3_u32 v0, 0, v160, v161
	ds_write_b128 v0, v[2:5]
	v_mad_u64_u32 v[2:3], s[4:5], v148, 48, v[0:1]
	v_lshrrev_b32_e32 v0, 2, v18
	v_lshlrev_b32_e32 v163, 2, v31
	ds_write_b128 v2, v[6:9] offset:34816
	v_and_or_b32 v0, v0, 3, v163
	v_lshlrev_b32_e32 v2, 1, v18
	v_lshlrev_b32_e32 v3, 3, v18
	s_add_i32 s5, s33, s60
	v_lshl_add_u32 v149, v31, 4, 0
	v_mad_u32_u24 v0, v0, s46, 0
	v_and_b32_e32 v2, 32, v2
	v_and_b32_e32 v3, 24, v3
	v_lshl_add_u32 v152, v148, 14, v14
	v_mov_b32_e32 v14, v1
	v_mov_b32_e32 v15, v1
	v_mad_u32_u24 v162, v30, s45, v149
	v_add3_u32 v164, v0, v2, v3
	v_lshl_add_u32 v150, v146, 14, v12
	s_mov_b64 s[78:79], s[20:21]
	v_add_u32_e32 v195, s5, v30
	v_mov_b32_e32 v0, v1
	v_mov_b32_e32 v2, v1
	v_mov_b32_e32 v3, v1
	v_mov_b32_e32 v4, v1
	v_mov_b32_e32 v5, v1
	v_mov_b32_e32 v6, v1
	v_mov_b32_e32 v7, v1
	v_mov_b32_e32 v8, v1
	v_mov_b32_e32 v9, v1
	v_mov_b32_e32 v10, v1
	v_mov_b32_e32 v11, v1
	v_mov_b32_e32 v12, v1
	v_mov_b32_e32 v13, v1
	v_mov_b64_e32 v[64:65], v[14:15]
	v_mov_b64_e32 v[48:49], v[14:15]
	v_mov_b64_e32 v[32:33], v[14:15]
	s_lshl_b32 s6, s51, 2
	s_lshl_b32 s7, s51, 10
	v_mov_b64_e32 v[62:63], v[12:13]
	v_mov_b64_e32 v[60:61], v[10:11]
	v_mov_b64_e32 v[58:59], v[8:9]
	v_mov_b64_e32 v[56:57], v[6:7]
	v_mov_b64_e32 v[54:55], v[4:5]
	v_mov_b64_e32 v[52:53], v[2:3]
	v_mov_b64_e32 v[50:51], v[0:1]
	v_mov_b64_e32 v[46:47], v[12:13]
	v_mov_b64_e32 v[44:45], v[10:11]
	v_mov_b64_e32 v[42:43], v[8:9]
	v_mov_b64_e32 v[40:41], v[6:7]
	v_mov_b64_e32 v[38:39], v[4:5]
	v_mov_b64_e32 v[36:37], v[2:3]
	v_mov_b64_e32 v[34:35], v[0:1]
	v_mov_b64_e32 v[30:31], v[12:13]
	v_mov_b64_e32 v[28:29], v[10:11]
	v_mov_b64_e32 v[26:27], v[8:9]
	v_mov_b64_e32 v[24:25], v[6:7]
	v_mov_b64_e32 v[22:23], v[4:5]
	v_mov_b64_e32 v[20:21], v[2:3]
	v_mov_b64_e32 v[18:19], v[0:1]
	v_mov_b64_e32 v[16:17], v[14:15]
	s_mov_b32 s0, 2
	s_add_i32 s1, s6, 4
	v_mul_lo_u32 v159, v146, s46
	v_mul_lo_u32 v147, v148, s46
	s_mov_b32 s4, 0
	s_or_b32 s6, s6, 3
	v_or_b32_e32 v165, 32, v163
	v_or_b32_e32 v166, 33, v163
	v_or_b32_e32 v167, 2, v163
	v_or_b32_e32 v168, 34, v163
	v_or_b32_e32 v169, 3, v163
	v_or_b32_e32 v170, 35, v163
	v_or_b32_e32 v171, 8, v163
	v_or_b32_e32 v172, 40, v163
	v_or_b32_e32 v173, 9, v163
	v_or_b32_e32 v174, 41, v163
	v_or_b32_e32 v175, 10, v163
	v_or_b32_e32 v176, 42, v163
	v_or_b32_e32 v177, 11, v163
	v_or_b32_e32 v178, 43, v163
	v_or_b32_e32 v179, 16, v163
	v_or_b32_e32 v180, 48, v163
	v_or_b32_e32 v181, 17, v163
	v_or_b32_e32 v182, 49, v163
	v_or_b32_e32 v183, 18, v163
	v_or_b32_e32 v184, 50, v163
	v_or_b32_e32 v185, 19, v163
	v_or_b32_e32 v186, 51, v163
	v_or_b32_e32 v187, 24, v163
	v_or_b32_e32 v188, 56, v163
	v_or_b32_e32 v189, 25, v163
	v_or_b32_e32 v190, 57, v163
	v_or_b32_e32 v191, 26, v163
	v_or_b32_e32 v192, 58, v163
	v_or_b32_e32 v193, 27, v163
	v_or_b32_e32 v194, 59, v163
	s_addk_i32 s7, 0x400
	v_mov_b32_e32 v196, 0
	v_mov_b32_e32 v197, 0xf149f2ca
	s_mov_b32 s26, 63
	v_mov_b64_e32 v[14:15], v[12:13]
	v_mov_b64_e32 v[12:13], v[10:11]
	v_mov_b64_e32 v[10:11], v[8:9]
	v_mov_b64_e32 v[8:9], v[6:7]
	v_mov_b64_e32 v[6:7], v[4:5]
	v_mov_b64_e32 v[4:5], v[2:3]
	v_mov_b64_e32 v[2:3], v[0:1]
	s_waitcnt lgkmcnt(0)
	s_movk_i32 s68, 0x5000
	s_mov_b32 s69, 0
	s_mov_b32 s70, 0xe800
	s_mov_b32 s72, 0
	s_lshl_b32 s77, s6, 6
	v_subrev_u32_e32 v195, s77, v195
	s_barrier
	v_readfirstlane_b32 s73, v255
	s_cmp_lt_u32 s73, 0x100
	s_cbranch_scc1 .Lyp649
	s_setprio 1

.LBB0_649:
	s_add_i32 s27, s0, -2
	s_and_b32 s27, s27, 1
	s_xor_b32 s34, s27, 1
	s_mul_i32 s35, s34, 0x4400
	s_add_i32 s35, s35, 0
	s_mulk_i32 s34, 0xc00
	s_add_i32 s34, s35, s34
	v_add3_u32 v0, s35, v157, v158
	s_waitcnt vmcnt(3)
	ds_write_b128 v0, v[130:133]
	v_add3_u32 v0, s68, v159, v158
	s_waitcnt vmcnt(2)
	ds_write_b128 v0, v[134:137] offset:34816
	v_add3_u32 v0, s35, v160, v161
	s_cmp_lt_u32 s0, s1
	s_waitcnt vmcnt(1)
	ds_write_b128 v0, v[138:141]
	v_add3_u32 v0, s68, v147, v161
	s_cselect_b32 s34, s0, s6
	s_sub_i32 s34, s6, s34
	s_lshl_b32 s34, s34, 20
	s_add_u32 s80, s78, s34
	s_addc_u32 s81, s79, 0
	s_add_u32 s80, s80, 0x1000
	s_addc_u32 s81, s81, 0
	s_add_u32 s82, s80, 0x1000
	s_addc_u32 s83, s81, 0
	s_waitcnt vmcnt(0)
	ds_write_b128 v0, v[142:145] offset:34816
	global_load_dwordx4 v[130:133], v150, s[80:81]
	global_load_dwordx4 v[134:137], v150, s[82:83]
	s_sub_i32 s34, s26, 63
	s_cmp_gt_i32 s34, s5
	global_load_dwordx4 v[138:141], v152, s[80:81]
	global_load_dwordx4 v[142:145], v152, s[82:83]
	s_lshr_b32 s77, s7, 2
	s_sub_i32 s77, s77, s26
	s_add_i32 s77, s77, -1
	s_sub_i32 s75, s7, s4
	s_add_i32 s75, s75, -256
	s_cmp_gt_i32 s77, s5
	s_cbranch_scc1 .Lff1a_inact
	s_cmp_eq_u32 s72, 0
	s_cbranch_scc1 .Lff1a_first
	s_mul_i32 s34, s27, 0x4400
	v_add_u32_e32 v0, s34, v162
	ds_read_b128 v[198:201], v0
	ds_read_b128 v[202:205], v0 offset:32
	ds_read_b128 v[206:209], v0 offset:8704
	ds_read_b128 v[210:213], v0 offset:8736
	v_add_u32_e32 v246, s75, v149
	v_add_u32_e32 v234, 0x12800, v246
	v_add_u32_e32 v235, 0x12880, v246
	v_add_u32_e32 v238, 0x12820, v246
	v_add_u32_e32 v239, 0x128a0, v246
	v_add_u32_e32 v242, 0x12840, v246
	v_add_u32_e32 v243, 0x128c0, v246
	v_add_u32_e32 v247, 0x12860, v246
	v_add_u32_e32 v246, 0x128e0, v246
	ds_read_b128 v[218:221], v234
	ds_read_b128 v[234:237], v235
	ds_read_b128 v[222:225], v238
	ds_read_b128 v[238:241], v239
	ds_read_b128 v[226:229], v242
	ds_read_b128 v[242:245], v243
	ds_read_b128 v[230:233], v247
	ds_read_b128 v[246:249], v246
	s_waitcnt lgkmcnt(1)
	v_mfma_f32_32x32x16_bf16 v[218:233], v[198:201], v[98:101], v[218:233]
	v_sub_f32_e32 v82, v82, v197
	v_sub_f32_e32 v83, v83, v197
	v_sub_f32_e32 v84, v84, v197
	v_sub_f32_e32 v85, v85, v197
	v_exp_f32_e32 v82, v82
	v_exp_f32_e32 v83, v83
	v_exp_f32_e32 v84, v84
	v_exp_f32_e32 v85, v85
	s_waitcnt lgkmcnt(0)
	v_mfma_f32_32x32x16_bf16 v[234:249], v[206:209], v[98:101], v[234:249]
	v_sub_f32_e32 v86, v86, v197
	v_sub_f32_e32 v87, v87, v197
	v_sub_f32_e32 v88, v88, v197
	v_sub_f32_e32 v89, v89, v197
	v_exp_f32_e32 v86, v86
	v_exp_f32_e32 v87, v87
	v_exp_f32_e32 v88, v88
	v_exp_f32_e32 v89, v89
	v_mfma_f32_32x32x16_bf16 v[218:233], v[202:205], v[102:105], v[218:233]
	v_sub_f32_e32 v66, v66, v197
	v_sub_f32_e32 v67, v67, v197
	v_sub_f32_e32 v68, v68, v197
	v_sub_f32_e32 v69, v69, v197
	v_exp_f32_e32 v66, v66
	v_exp_f32_e32 v67, v67
	v_exp_f32_e32 v68, v68
	v_exp_f32_e32 v69, v69
	ds_read_b128 v[198:201], v0 offset:64
	ds_read_b128 v[202:205], v0 offset:96
	ds_read_b128 v[206:209], v0 offset:8768
	ds_read_b128 v[214:217], v0 offset:8800
	v_mfma_f32_32x32x16_bf16 v[234:249], v[210:213], v[102:105], v[234:249]
	v_add_f32_e32 v250, v82, v86
	v_add_f32_e32 v251, v83, v87
	v_add_f32_e32 v252, v84, v88
	v_add_f32_e32 v253, v85, v89
	v_sub_f32_e32 v70, v70, v197
	v_sub_f32_e32 v71, v71, v197
	v_sub_f32_e32 v72, v72, v197
	v_sub_f32_e32 v73, v73, v197
	s_waitcnt lgkmcnt(3)
	v_mfma_f32_32x32x16_bf16 v[218:233], v[198:201], v[106:109], v[218:233]
	v_exp_f32_e32 v70, v70
	v_exp_f32_e32 v71, v71
	v_exp_f32_e32 v72, v72
	v_exp_f32_e32 v73, v73
	v_add_f32_e32 v250, v250, v66
	v_add_f32_e32 v251, v251, v67
	v_add_f32_e32 v252, v252, v68
	v_add_f32_e32 v253, v253, v69
	s_waitcnt lgkmcnt(1)
	v_mfma_f32_32x32x16_bf16 v[234:249], v[206:209], v[106:109], v[234:249]
	v_sub_f32_e32 v90, v90, v197
	v_sub_f32_e32 v91, v91, v197
	v_sub_f32_e32 v92, v92, v197
	v_sub_f32_e32 v93, v93, v197
	v_exp_f32_e32 v90, v90
	v_exp_f32_e32 v91, v91
	v_exp_f32_e32 v92, v92
	v_exp_f32_e32 v93, v93
	v_mfma_f32_32x32x16_bf16 v[218:233], v[202:205], v[110:113], v[218:233]
	v_add_f32_e32 v250, v250, v70
	v_add_f32_e32 v251, v251, v71
	v_add_f32_e32 v252, v252, v72
	v_add_f32_e32 v253, v253, v73
	v_sub_f32_e32 v94, v94, v197
	v_sub_f32_e32 v95, v95, v197
	v_sub_f32_e32 v96, v96, v197
	v_sub_f32_e32 v97, v97, v197
	ds_read_b128 v[198:201], v0 offset:128
	ds_read_b128 v[202:205], v0 offset:160
	ds_read_b128 v[206:209], v0 offset:8832
	ds_read_b128 v[210:213], v0 offset:8864
	s_waitcnt lgkmcnt(4)
	v_mfma_f32_32x32x16_bf16 v[234:249], v[214:217], v[110:113], v[234:249]
	v_exp_f32_e32 v94, v94
	v_exp_f32_e32 v95, v95
	v_exp_f32_e32 v96, v96
	v_exp_f32_e32 v97, v97
	v_add_f32_e32 v250, v250, v90
	v_add_f32_e32 v251, v251, v91
	v_add_f32_e32 v252, v252, v92
	v_add_f32_e32 v253, v253, v93
	s_waitcnt lgkmcnt(3)
	v_mfma_f32_32x32x16_bf16 v[218:233], v[198:201], v[114:117], v[218:233]
	v_sub_f32_e32 v74, v74, v197
	v_sub_f32_e32 v75, v75, v197
	v_sub_f32_e32 v76, v76, v197
	v_sub_f32_e32 v77, v77, v197
	v_exp_f32_e32 v74, v74
	v_exp_f32_e32 v75, v75
	v_exp_f32_e32 v76, v76
	v_exp_f32_e32 v77, v77
	s_waitcnt lgkmcnt(1)
	v_mfma_f32_32x32x16_bf16 v[234:249], v[206:209], v[114:117], v[234:249]
	v_add_f32_e32 v250, v250, v94
	v_add_f32_e32 v251, v251, v95
	v_add_f32_e32 v252, v252, v96
	v_add_f32_e32 v253, v253, v97
	v_sub_f32_e32 v78, v78, v197
	v_sub_f32_e32 v79, v79, v197
	v_sub_f32_e32 v80, v80, v197
	v_sub_f32_e32 v81, v81, v197
	v_mfma_f32_32x32x16_bf16 v[218:233], v[202:205], v[118:121], v[218:233]
	v_exp_f32_e32 v78, v78
	v_exp_f32_e32 v79, v79
	v_exp_f32_e32 v80, v80
	v_exp_f32_e32 v81, v81
	v_add_f32_e32 v250, v250, v74
	v_add_f32_e32 v251, v251, v75
	v_add_f32_e32 v252, v252, v76
	v_add_f32_e32 v253, v253, v77
	ds_read_b128 v[198:201], v0 offset:192
	ds_read_b128 v[202:205], v0 offset:224
	ds_read_b128 v[206:209], v0 offset:8896
	ds_read_b128 v[214:217], v0 offset:8928
	s_waitcnt lgkmcnt(4)
	v_mfma_f32_32x32x16_bf16 v[234:249], v[210:213], v[118:121], v[234:249]
	v_add_f32_e32 v250, v250, v78
	v_add_f32_e32 v251, v251, v79
	v_add_f32_e32 v252, v252, v80
	v_add_f32_e32 v253, v253, v81
	v_add_f32_e32 v250, v250, v251
	v_add_f32_e32 v252, v252, v253
	v_add_f32_e32 v250, v250, v252
	v_add_f32_e32 v196, v196, v250
	s_waitcnt lgkmcnt(3)
	v_mfma_f32_32x32x16_bf16 v[218:233], v[198:201], v[122:125], v[218:233]
	v_cvt_pk_bf16_f32 v73, v72, v73
	v_cvt_pk_bf16_f32 v72, v70, v71
	v_cvt_pk_bf16_f32 v71, v68, v69
	v_cvt_pk_bf16_f32 v70, v66, v67
	v_cvt_pk_bf16_f32 v66, v82, v83
	v_cvt_pk_bf16_f32 v67, v84, v85
	v_cvt_pk_bf16_f32 v68, v86, v87
	v_cvt_pk_bf16_f32 v69, v88, v89
	s_waitcnt lgkmcnt(1)
	v_mfma_f32_32x32x16_bf16 v[234:249], v[206:209], v[122:125], v[234:249]
	v_cvt_pk_bf16_f32 v81, v80, v81
	v_cvt_pk_bf16_f32 v80, v78, v79
	v_cvt_pk_bf16_f32 v79, v76, v77
	v_cvt_pk_bf16_f32 v78, v74, v75
	v_cvt_pk_bf16_f32 v74, v90, v91
	v_cvt_pk_bf16_f32 v75, v92, v93
	v_cvt_pk_bf16_f32 v76, v94, v95
	v_cvt_pk_bf16_f32 v77, v96, v97
	v_mfma_f32_32x32x16_bf16 v[218:233], v[202:205], v[126:129], v[218:233]
	s_waitcnt lgkmcnt(0)
	v_mfma_f32_32x32x16_bf16 v[234:249], v[214:217], v[126:129], v[234:249]
	s_add_i32 s76, s77, 63
	s_cmp_le_i32 s76, s5
	s_cbranch_scc1 .Lff1a_z2
	v_cmp_le_i32_e32 vcc, v165, v195
	s_nop 8
	v_cndmask_b32_e32 v234, v155, v234, vcc
	v_cmp_lt_i32_e32 vcc, v163, v195
	s_nop 1
	v_cndmask_b32_e32 v219, v155, v219, vcc
	v_cmp_le_i32_e32 vcc, v163, v195
	s_nop 1
	v_cndmask_b32_e32 v218, v155, v218, vcc
	v_cmp_le_i32_e32 vcc, v166, v195
	s_nop 1
	v_cndmask_b32_e32 v235, v155, v235, vcc
	v_cmp_le_i32_e32 vcc, v167, v195
	s_nop 1
	v_cndmask_b32_e32 v220, v155, v220, vcc
	v_cmp_le_i32_e32 vcc, v168, v195
	s_nop 1
	v_cndmask_b32_e32 v236, v155, v236, vcc
	v_cmp_le_i32_e32 vcc, v169, v195
	s_nop 1
	v_cndmask_b32_e32 v221, v155, v221, vcc
	v_cmp_le_i32_e32 vcc, v170, v195
	s_nop 1
	v_cndmask_b32_e32 v237, v155, v237, vcc
	v_cmp_le_i32_e32 vcc, v171, v195
	s_nop 1
	v_cndmask_b32_e32 v222, v155, v222, vcc
	v_cmp_le_i32_e32 vcc, v172, v195
	s_nop 1
	v_cndmask_b32_e32 v238, v155, v238, vcc
	v_cmp_le_i32_e32 vcc, v173, v195
	s_nop 1
	v_cndmask_b32_e32 v223, v155, v223, vcc
	v_cmp_le_i32_e32 vcc, v174, v195
	s_nop 1
	v_cndmask_b32_e32 v239, v155, v239, vcc
	v_cmp_le_i32_e32 vcc, v175, v195
	s_nop 1
	v_cndmask_b32_e32 v224, v155, v224, vcc
	v_cmp_le_i32_e32 vcc, v176, v195
	s_nop 1
	v_cndmask_b32_e32 v240, v155, v240, vcc
	v_cmp_le_i32_e32 vcc, v177, v195
	s_nop 1
	v_cndmask_b32_e32 v225, v155, v225, vcc
	v_cmp_le_i32_e32 vcc, v178, v195
	s_nop 1
	v_cndmask_b32_e32 v241, v155, v241, vcc
	v_cmp_le_i32_e32 vcc, v179, v195
	s_nop 1
	v_cndmask_b32_e32 v226, v155, v226, vcc
	v_cmp_le_i32_e32 vcc, v180, v195
	s_nop 1
	v_cndmask_b32_e32 v242, v155, v242, vcc
	v_cmp_le_i32_e32 vcc, v181, v195
	s_nop 1
	v_cndmask_b32_e32 v227, v155, v227, vcc
	v_cmp_le_i32_e32 vcc, v182, v195
	s_nop 1
	v_cndmask_b32_e32 v243, v155, v243, vcc
	v_cmp_le_i32_e32 vcc, v183, v195
	s_nop 1
	v_cndmask_b32_e32 v228, v155, v228, vcc
	v_cmp_le_i32_e32 vcc, v184, v195
	s_nop 1
	v_cndmask_b32_e32 v244, v155, v244, vcc
	v_cmp_le_i32_e32 vcc, v185, v195
	s_nop 1
	v_cndmask_b32_e32 v229, v155, v229, vcc
	v_cmp_le_i32_e32 vcc, v186, v195
	s_nop 1
	v_cndmask_b32_e32 v245, v155, v245, vcc
	v_cmp_le_i32_e32 vcc, v187, v195
	s_nop 1
	v_cndmask_b32_e32 v230, v155, v230, vcc
	v_cmp_le_i32_e32 vcc, v188, v195
	s_nop 1
	v_cndmask_b32_e32 v246, v155, v246, vcc
	v_cmp_le_i32_e32 vcc, v189, v195
	s_nop 1
	v_cndmask_b32_e32 v231, v155, v231, vcc
	v_cmp_le_i32_e32 vcc, v190, v195
	s_nop 1
	v_cndmask_b32_e32 v247, v155, v247, vcc
	v_cmp_le_i32_e32 vcc, v191, v195
	s_nop 1
	v_cndmask_b32_e32 v232, v155, v232, vcc
	v_cmp_le_i32_e32 vcc, v192, v195
	s_nop 1
	v_cndmask_b32_e32 v248, v155, v248, vcc
	v_cmp_le_i32_e32 vcc, v193, v195
	s_nop 1
	v_cndmask_b32_e32 v233, v155, v233, vcc
	v_cmp_le_i32_e32 vcc, v194, v195
	s_nop 1
	v_cndmask_b32_e32 v249, v155, v249, vcc

.Lff1a_first:
	s_mul_i32 s34, s27, 0x4400
	v_add_u32_e32 v0, s34, v162
	ds_read_b128 v[198:201], v0
	ds_read_b128 v[202:205], v0 offset:32
	ds_read_b128 v[206:209], v0 offset:8704
	ds_read_b128 v[210:213], v0 offset:8736
	v_add_u32_e32 v246, s75, v149
	v_add_u32_e32 v234, 0x12800, v246
	v_add_u32_e32 v235, 0x12880, v246
	v_add_u32_e32 v238, 0x12820, v246
	v_add_u32_e32 v239, 0x128a0, v246
	v_add_u32_e32 v242, 0x12840, v246
	v_add_u32_e32 v243, 0x128c0, v246
	v_add_u32_e32 v247, 0x12860, v246
	v_add_u32_e32 v246, 0x128e0, v246
	ds_read_b128 v[218:221], v234
	ds_read_b128 v[234:237], v235
	ds_read_b128 v[222:225], v238
	ds_read_b128 v[238:241], v239
	ds_read_b128 v[226:229], v242
	ds_read_b128 v[242:245], v243
	ds_read_b128 v[230:233], v247
	ds_read_b128 v[246:249], v246
	s_waitcnt lgkmcnt(1)
	v_mfma_f32_32x32x16_bf16 v[218:233], v[198:201], v[98:101], v[218:233]
	s_waitcnt lgkmcnt(0)
	v_mfma_f32_32x32x16_bf16 v[234:249], v[206:209], v[98:101], v[234:249]
	v_mfma_f32_32x32x16_bf16 v[218:233], v[202:205], v[102:105], v[218:233]
	ds_read_b128 v[198:201], v0 offset:64
	ds_read_b128 v[202:205], v0 offset:96
	ds_read_b128 v[206:209], v0 offset:8768
	ds_read_b128 v[214:217], v0 offset:8800
	v_mfma_f32_32x32x16_bf16 v[234:249], v[210:213], v[102:105], v[234:249]
	s_waitcnt lgkmcnt(3)
	v_mfma_f32_32x32x16_bf16 v[218:233], v[198:201], v[106:109], v[218:233]
	s_waitcnt lgkmcnt(1)
	v_mfma_f32_32x32x16_bf16 v[234:249], v[206:209], v[106:109], v[234:249]
	v_mfma_f32_32x32x16_bf16 v[218:233], v[202:205], v[110:113], v[218:233]
	ds_read_b128 v[198:201], v0 offset:128
	ds_read_b128 v[202:205], v0 offset:160
	ds_read_b128 v[206:209], v0 offset:8832
	ds_read_b128 v[210:213], v0 offset:8864
	s_waitcnt lgkmcnt(4)
	v_mfma_f32_32x32x16_bf16 v[234:249], v[214:217], v[110:113], v[234:249]
	s_waitcnt lgkmcnt(3)
	v_mfma_f32_32x32x16_bf16 v[218:233], v[198:201], v[114:117], v[218:233]
	s_waitcnt lgkmcnt(1)
	v_mfma_f32_32x32x16_bf16 v[234:249], v[206:209], v[114:117], v[234:249]
	v_mfma_f32_32x32x16_bf16 v[218:233], v[202:205], v[118:121], v[218:233]
	ds_read_b128 v[198:201], v0 offset:192
	ds_read_b128 v[202:205], v0 offset:224
	ds_read_b128 v[206:209], v0 offset:8896
	ds_read_b128 v[214:217], v0 offset:8928
	s_waitcnt lgkmcnt(4)
	v_mfma_f32_32x32x16_bf16 v[234:249], v[210:213], v[118:121], v[234:249]
	s_waitcnt lgkmcnt(3)
	v_mfma_f32_32x32x16_bf16 v[218:233], v[198:201], v[122:125], v[218:233]
	s_waitcnt lgkmcnt(1)
	v_mfma_f32_32x32x16_bf16 v[234:249], v[206:209], v[122:125], v[234:249]
	v_mfma_f32_32x32x16_bf16 v[218:233], v[202:205], v[126:129], v[218:233]
	s_waitcnt lgkmcnt(0)
	v_mfma_f32_32x32x16_bf16 v[234:249], v[214:217], v[126:129], v[234:249]
	s_add_i32 s76, s77, 63
	s_cmp_le_i32 s76, s5
	s_cbranch_scc1 .Lff1a_m1
	v_cmp_le_i32_e32 vcc, v165, v195
	s_nop 8
	v_cndmask_b32_e32 v234, v155, v234, vcc
	v_cmp_lt_i32_e32 vcc, v163, v195
	s_nop 1
	v_cndmask_b32_e32 v219, v155, v219, vcc
	v_cmp_le_i32_e32 vcc, v163, v195
	s_nop 1
	v_cndmask_b32_e32 v218, v155, v218, vcc
	v_cmp_le_i32_e32 vcc, v166, v195
	s_nop 1
	v_cndmask_b32_e32 v235, v155, v235, vcc
	v_cmp_le_i32_e32 vcc, v167, v195
	s_nop 1
	v_cndmask_b32_e32 v220, v155, v220, vcc
	v_cmp_le_i32_e32 vcc, v168, v195
	s_nop 1
	v_cndmask_b32_e32 v236, v155, v236, vcc
	v_cmp_le_i32_e32 vcc, v169, v195
	s_nop 1
	v_cndmask_b32_e32 v221, v155, v221, vcc
	v_cmp_le_i32_e32 vcc, v170, v195
	s_nop 1
	v_cndmask_b32_e32 v237, v155, v237, vcc
	v_cmp_le_i32_e32 vcc, v171, v195
	s_nop 1
	v_cndmask_b32_e32 v222, v155, v222, vcc
	v_cmp_le_i32_e32 vcc, v172, v195
	s_nop 1
	v_cndmask_b32_e32 v238, v155, v238, vcc
	v_cmp_le_i32_e32 vcc, v173, v195
	s_nop 1
	v_cndmask_b32_e32 v223, v155, v223, vcc
	v_cmp_le_i32_e32 vcc, v174, v195
	s_nop 1
	v_cndmask_b32_e32 v239, v155, v239, vcc
	v_cmp_le_i32_e32 vcc, v175, v195
	s_nop 1
	v_cndmask_b32_e32 v224, v155, v224, vcc
	v_cmp_le_i32_e32 vcc, v176, v195
	s_nop 1
	v_cndmask_b32_e32 v240, v155, v240, vcc
	v_cmp_le_i32_e32 vcc, v177, v195
	s_nop 1
	v_cndmask_b32_e32 v225, v155, v225, vcc
	v_cmp_le_i32_e32 vcc, v178, v195
	s_nop 1
	v_cndmask_b32_e32 v241, v155, v241, vcc
	v_cmp_le_i32_e32 vcc, v179, v195
	s_nop 1
	v_cndmask_b32_e32 v226, v155, v226, vcc
	v_cmp_le_i32_e32 vcc, v180, v195
	s_nop 1
	v_cndmask_b32_e32 v242, v155, v242, vcc
	v_cmp_le_i32_e32 vcc, v181, v195
	s_nop 1
	v_cndmask_b32_e32 v227, v155, v227, vcc
	v_cmp_le_i32_e32 vcc, v182, v195
	s_nop 1
	v_cndmask_b32_e32 v243, v155, v243, vcc
	v_cmp_le_i32_e32 vcc, v183, v195
	s_nop 1
	v_cndmask_b32_e32 v228, v155, v228, vcc
	v_cmp_le_i32_e32 vcc, v184, v195
	s_nop 1
	v_cndmask_b32_e32 v244, v155, v244, vcc
	v_cmp_le_i32_e32 vcc, v185, v195
	s_nop 1
	v_cndmask_b32_e32 v229, v155, v229, vcc
	v_cmp_le_i32_e32 vcc, v186, v195
	s_nop 1
	v_cndmask_b32_e32 v245, v155, v245, vcc
	v_cmp_le_i32_e32 vcc, v187, v195
	s_nop 1
	v_cndmask_b32_e32 v230, v155, v230, vcc
	v_cmp_le_i32_e32 vcc, v188, v195
	s_nop 1
	v_cndmask_b32_e32 v246, v155, v246, vcc
	v_cmp_le_i32_e32 vcc, v189, v195
	s_nop 1
	v_cndmask_b32_e32 v231, v155, v231, vcc
	v_cmp_le_i32_e32 vcc, v190, v195
	s_nop 1
	v_cndmask_b32_e32 v247, v155, v247, vcc
	v_cmp_le_i32_e32 vcc, v191, v195
	s_nop 1
	v_cndmask_b32_e32 v232, v155, v232, vcc
	v_cmp_le_i32_e32 vcc, v192, v195
	s_nop 1
	v_cndmask_b32_e32 v248, v155, v248, vcc
	v_cmp_le_i32_e32 vcc, v193, v195
	s_nop 1
	v_cndmask_b32_e32 v233, v155, v233, vcc
	v_cmp_le_i32_e32 vcc, v194, v195
	s_nop 1
	v_cndmask_b32_e32 v249, v155, v249, vcc

.Lff1a_copy:
	s_nop 7
	v_add_f32_e32 v252, 0xc3180000, v197
	v_cmp_lt_f32_e64 s[84:85], v0, v252
	s_cbranch_vccz .Lff1a_norsc
	v_max_f32_e32 v0, v0, v0
	v_max_f32_e32 v251, v197, v197
	v_max_f32_e32 v251, v251, v0
	v_sub_f32_e32 v252, v197, v251
	v_exp_f32_e32 v252, v252
	v_mov_b32_e32 v197, v251
	s_nop 0
	v_mul_f32_e32 v196, v196, v252
	s_nop 1
	v_pk_mul_f32 v[64:65], v[64:65], v[252:253] op_sel_hi:[1,0]
	v_pk_mul_f32 v[62:63], v[62:63], v[252:253] op_sel_hi:[1,0]
	v_pk_mul_f32 v[60:61], v[60:61], v[252:253] op_sel_hi:[1,0]
	v_pk_mul_f32 v[58:59], v[58:59], v[252:253] op_sel_hi:[1,0]
	v_pk_mul_f32 v[56:57], v[56:57], v[252:253] op_sel_hi:[1,0]
	v_pk_mul_f32 v[54:55], v[54:55], v[252:253] op_sel_hi:[1,0]
	v_pk_mul_f32 v[52:53], v[52:53], v[252:253] op_sel_hi:[1,0]
	v_pk_mul_f32 v[50:51], v[50:51], v[252:253] op_sel_hi:[1,0]
	v_pk_mul_f32 v[48:49], v[48:49], v[252:253] op_sel_hi:[1,0]
	v_pk_mul_f32 v[46:47], v[46:47], v[252:253] op_sel_hi:[1,0]
	v_pk_mul_f32 v[44:45], v[44:45], v[252:253] op_sel_hi:[1,0]
	v_pk_mul_f32 v[42:43], v[42:43], v[252:253] op_sel_hi:[1,0]
	v_pk_mul_f32 v[40:41], v[40:41], v[252:253] op_sel_hi:[1,0]
	v_pk_mul_f32 v[38:39], v[38:39], v[252:253] op_sel_hi:[1,0]
	v_pk_mul_f32 v[36:37], v[36:37], v[252:253] op_sel_hi:[1,0]
	v_pk_mul_f32 v[34:35], v[34:35], v[252:253] op_sel_hi:[1,0]
	v_pk_mul_f32 v[32:33], v[32:33], v[252:253] op_sel_hi:[1,0]
	v_pk_mul_f32 v[30:31], v[30:31], v[252:253] op_sel_hi:[1,0]
	v_pk_mul_f32 v[28:29], v[28:29], v[252:253] op_sel_hi:[1,0]
	v_pk_mul_f32 v[26:27], v[26:27], v[252:253] op_sel_hi:[1,0]
	v_pk_mul_f32 v[24:25], v[24:25], v[252:253] op_sel_hi:[1,0]
	v_pk_mul_f32 v[22:23], v[22:23], v[252:253] op_sel_hi:[1,0]
	v_pk_mul_f32 v[20:21], v[20:21], v[252:253] op_sel_hi:[1,0]
	v_pk_mul_f32 v[18:19], v[18:19], v[252:253] op_sel_hi:[1,0]
	v_pk_mul_f32 v[16:17], v[16:17], v[252:253] op_sel_hi:[1,0]
	v_pk_mul_f32 v[14:15], v[14:15], v[252:253] op_sel_hi:[1,0]
	v_pk_mul_f32 v[12:13], v[12:13], v[252:253] op_sel_hi:[1,0]
	v_pk_mul_f32 v[10:11], v[10:11], v[252:253] op_sel_hi:[1,0]
	v_pk_mul_f32 v[8:9], v[8:9], v[252:253] op_sel_hi:[1,0]
	v_pk_mul_f32 v[6:7], v[6:7], v[252:253] op_sel_hi:[1,0]
	v_pk_mul_f32 v[4:5], v[4:5], v[252:253] op_sel_hi:[1,0]
	v_pk_mul_f32 v[2:3], v[2:3], v[252:253] op_sel_hi:[1,0]
.Lff1a_norsc:
	s_cmp_eq_u64 s[84:85], exec
	s_cselect_b32 s72, 0, 1
	s_branch .Lff1a_bar

.Lff1a_bar:
	s_waitcnt lgkmcnt(0)
	s_barrier
	s_mov_b32 s71, s70
	s_mov_b32 s70, s69
	s_mov_b32 s69, s68
	s_mov_b32 s68, s71
	s_addk_i32 s4, 0x100
	s_add_i32 s26, s26, 64
	s_add_i32 s0, s0, 1
	s_cmp_lg_u32 s7, s4
	v_add_u32_e32 v195, 64, v195
	s_cbranch_scc0 .Lff1a_exit
	s_branch .Lff1b_top

.Lff1b_top:
	s_add_i32 s27, s0, -2
	s_and_b32 s27, s27, 1
	s_xor_b32 s34, s27, 1
	s_mul_i32 s35, s34, 0x4400
	s_add_i32 s35, s35, 0
	s_mulk_i32 s34, 0xc00
	s_add_i32 s34, s35, s34
	v_add3_u32 v0, s35, v157, v158
	s_waitcnt vmcnt(3)
	ds_write_b128 v0, v[130:133]
	v_add3_u32 v0, s68, v159, v158
	s_waitcnt vmcnt(2)
	ds_write_b128 v0, v[134:137] offset:34816
	v_add3_u32 v0, s35, v160, v161
	s_cmp_lt_u32 s0, s1
	s_waitcnt vmcnt(1)
	ds_write_b128 v0, v[138:141]
	v_add3_u32 v0, s68, v147, v161
	s_cselect_b32 s34, s0, s6
	s_sub_i32 s34, s6, s34
	s_lshl_b32 s34, s34, 20
	s_add_u32 s80, s78, s34
	s_addc_u32 s81, s79, 0
	s_add_u32 s80, s80, 0x1000
	s_addc_u32 s81, s81, 0
	s_add_u32 s82, s80, 0x1000
	s_addc_u32 s83, s81, 0
	s_waitcnt vmcnt(0)
	ds_write_b128 v0, v[142:145] offset:34816
	global_load_dwordx4 v[130:133], v150, s[80:81]
	global_load_dwordx4 v[134:137], v150, s[82:83]
	s_sub_i32 s34, s26, 63
	s_cmp_gt_i32 s34, s5
	global_load_dwordx4 v[138:141], v152, s[80:81]
	global_load_dwordx4 v[142:145], v152, s[82:83]
	s_lshr_b32 s77, s7, 2
	s_sub_i32 s77, s77, s26
	s_add_i32 s77, s77, -1
	s_sub_i32 s75, s7, s4
	s_add_i32 s75, s75, -256
	s_cmp_gt_i32 s77, s5
	s_cbranch_scc1 .Lff1b_inact
	s_cmp_eq_u32 s72, 0
	s_cbranch_scc1 .Lff1b_first
	s_mul_i32 s34, s27, 0x4400
	v_add_u32_e32 v0, s34, v162
	ds_read_b128 v[198:201], v0
	ds_read_b128 v[202:205], v0 offset:32
	ds_read_b128 v[206:209], v0 offset:8704
	ds_read_b128 v[210:213], v0 offset:8736
	v_add_u32_e32 v78, s75, v149
	v_add_u32_e32 v66, 0x12800, v78
	v_add_u32_e32 v67, 0x12880, v78
	v_add_u32_e32 v70, 0x12820, v78
	v_add_u32_e32 v71, 0x128a0, v78
	v_add_u32_e32 v74, 0x12840, v78
	v_add_u32_e32 v75, 0x128c0, v78
	v_add_u32_e32 v79, 0x12860, v78
	v_add_u32_e32 v78, 0x128e0, v78
	ds_read_b128 v[82:85], v66
	ds_read_b128 v[66:69], v67
	ds_read_b128 v[86:89], v70
	ds_read_b128 v[70:73], v71
	ds_read_b128 v[90:93], v74
	ds_read_b128 v[74:77], v75
	ds_read_b128 v[94:97], v79
	ds_read_b128 v[78:81], v78
	s_waitcnt lgkmcnt(1)
	v_mfma_f32_32x32x16_bf16 v[82:97], v[198:201], v[98:101], v[82:97]
	v_sub_f32_e32 v218, v218, v197
	v_sub_f32_e32 v219, v219, v197
	v_sub_f32_e32 v220, v220, v197
	v_sub_f32_e32 v221, v221, v197
	v_exp_f32_e32 v218, v218
	v_exp_f32_e32 v219, v219
	v_exp_f32_e32 v220, v220
	v_exp_f32_e32 v221, v221
	s_waitcnt lgkmcnt(0)
	v_mfma_f32_32x32x16_bf16 v[66:81], v[206:209], v[98:101], v[66:81]
	v_sub_f32_e32 v222, v222, v197
	v_sub_f32_e32 v223, v223, v197
	v_sub_f32_e32 v224, v224, v197
	v_sub_f32_e32 v225, v225, v197
	v_exp_f32_e32 v222, v222
	v_exp_f32_e32 v223, v223
	v_exp_f32_e32 v224, v224
	v_exp_f32_e32 v225, v225
	v_mfma_f32_32x32x16_bf16 v[82:97], v[202:205], v[102:105], v[82:97]
	v_sub_f32_e32 v234, v234, v197
	v_sub_f32_e32 v235, v235, v197
	v_sub_f32_e32 v236, v236, v197
	v_sub_f32_e32 v237, v237, v197
	v_exp_f32_e32 v234, v234
	v_exp_f32_e32 v235, v235
	v_exp_f32_e32 v236, v236
	v_exp_f32_e32 v237, v237
	ds_read_b128 v[198:201], v0 offset:64
	ds_read_b128 v[202:205], v0 offset:96
	ds_read_b128 v[206:209], v0 offset:8768
	ds_read_b128 v[214:217], v0 offset:8800
	v_mfma_f32_32x32x16_bf16 v[66:81], v[210:213], v[102:105], v[66:81]
	v_add_f32_e32 v250, v218, v222
	v_add_f32_e32 v251, v219, v223
	v_add_f32_e32 v252, v220, v224
	v_add_f32_e32 v253, v221, v225
	v_sub_f32_e32 v238, v238, v197
	v_sub_f32_e32 v239, v239, v197
	v_sub_f32_e32 v240, v240, v197
	v_sub_f32_e32 v241, v241, v197
	s_waitcnt lgkmcnt(3)
	v_mfma_f32_32x32x16_bf16 v[82:97], v[198:201], v[106:109], v[82:97]
	v_exp_f32_e32 v238, v238
	v_exp_f32_e32 v239, v239
	v_exp_f32_e32 v240, v240
	v_exp_f32_e32 v241, v241
	v_add_f32_e32 v250, v250, v234
	v_add_f32_e32 v251, v251, v235
	v_add_f32_e32 v252, v252, v236
	v_add_f32_e32 v253, v253, v237
	s_waitcnt lgkmcnt(1)
	v_mfma_f32_32x32x16_bf16 v[66:81], v[206:209], v[106:109], v[66:81]
	v_sub_f32_e32 v226, v226, v197
	v_sub_f32_e32 v227, v227, v197
	v_sub_f32_e32 v228, v228, v197
	v_sub_f32_e32 v229, v229, v197
	v_exp_f32_e32 v226, v226
	v_exp_f32_e32 v227, v227
	v_exp_f32_e32 v228, v228
	v_exp_f32_e32 v229, v229
	v_mfma_f32_32x32x16_bf16 v[82:97], v[202:205], v[110:113], v[82:97]
	v_add_f32_e32 v250, v250, v238
	v_add_f32_e32 v251, v251, v239
	v_add_f32_e32 v252, v252, v240
	v_add_f32_e32 v253, v253, v241
	v_sub_f32_e32 v230, v230, v197
	v_sub_f32_e32 v231, v231, v197
	v_sub_f32_e32 v232, v232, v197
	v_sub_f32_e32 v233, v233, v197
	ds_read_b128 v[198:201], v0 offset:128
	ds_read_b128 v[202:205], v0 offset:160
	ds_read_b128 v[206:209], v0 offset:8832
	ds_read_b128 v[210:213], v0 offset:8864
	s_waitcnt lgkmcnt(4)
	v_mfma_f32_32x32x16_bf16 v[66:81], v[214:217], v[110:113], v[66:81]
	v_exp_f32_e32 v230, v230
	v_exp_f32_e32 v231, v231
	v_exp_f32_e32 v232, v232
	v_exp_f32_e32 v233, v233
	v_add_f32_e32 v250, v250, v226
	v_add_f32_e32 v251, v251, v227
	v_add_f32_e32 v252, v252, v228
	v_add_f32_e32 v253, v253, v229
	s_waitcnt lgkmcnt(3)
	v_mfma_f32_32x32x16_bf16 v[82:97], v[198:201], v[114:117], v[82:97]
	v_sub_f32_e32 v242, v242, v197
	v_sub_f32_e32 v243, v243, v197
	v_sub_f32_e32 v244, v244, v197
	v_sub_f32_e32 v245, v245, v197
	v_exp_f32_e32 v242, v242
	v_exp_f32_e32 v243, v243
	v_exp_f32_e32 v244, v244
	v_exp_f32_e32 v245, v245
	s_waitcnt lgkmcnt(1)
	v_mfma_f32_32x32x16_bf16 v[66:81], v[206:209], v[114:117], v[66:81]
	v_add_f32_e32 v250, v250, v230
	v_add_f32_e32 v251, v251, v231
	v_add_f32_e32 v252, v252, v232
	v_add_f32_e32 v253, v253, v233
	v_sub_f32_e32 v246, v246, v197
	v_sub_f32_e32 v247, v247, v197
	v_sub_f32_e32 v248, v248, v197
	v_sub_f32_e32 v249, v249, v197
	v_mfma_f32_32x32x16_bf16 v[82:97], v[202:205], v[118:121], v[82:97]
	v_exp_f32_e32 v246, v246
	v_exp_f32_e32 v247, v247
	v_exp_f32_e32 v248, v248
	v_exp_f32_e32 v249, v249
	v_add_f32_e32 v250, v250, v242
	v_add_f32_e32 v251, v251, v243
	v_add_f32_e32 v252, v252, v244
	v_add_f32_e32 v253, v253, v245
	ds_read_b128 v[198:201], v0 offset:192
	ds_read_b128 v[202:205], v0 offset:224
	ds_read_b128 v[206:209], v0 offset:8896
	ds_read_b128 v[214:217], v0 offset:8928
	s_waitcnt lgkmcnt(4)
	v_mfma_f32_32x32x16_bf16 v[66:81], v[210:213], v[118:121], v[66:81]
	v_add_f32_e32 v250, v250, v246
	v_add_f32_e32 v251, v251, v247
	v_add_f32_e32 v252, v252, v248
	v_add_f32_e32 v253, v253, v249
	v_add_f32_e32 v250, v250, v251
	v_add_f32_e32 v252, v252, v253
	v_add_f32_e32 v250, v250, v252
	v_add_f32_e32 v196, v196, v250
	s_waitcnt lgkmcnt(3)
	v_mfma_f32_32x32x16_bf16 v[82:97], v[198:201], v[122:125], v[82:97]
	v_cvt_pk_bf16_f32 v241, v240, v241
	v_cvt_pk_bf16_f32 v240, v238, v239
	v_cvt_pk_bf16_f32 v239, v236, v237
	v_cvt_pk_bf16_f32 v238, v234, v235
	v_cvt_pk_bf16_f32 v234, v218, v219
	v_cvt_pk_bf16_f32 v235, v220, v221
	v_cvt_pk_bf16_f32 v236, v222, v223
	v_cvt_pk_bf16_f32 v237, v224, v225
	s_waitcnt lgkmcnt(1)
	v_mfma_f32_32x32x16_bf16 v[66:81], v[206:209], v[122:125], v[66:81]
	v_cvt_pk_bf16_f32 v249, v248, v249
	v_cvt_pk_bf16_f32 v248, v246, v247
	v_cvt_pk_bf16_f32 v247, v244, v245
	v_cvt_pk_bf16_f32 v246, v242, v243
	v_cvt_pk_bf16_f32 v242, v226, v227
	v_cvt_pk_bf16_f32 v243, v228, v229
	v_cvt_pk_bf16_f32 v244, v230, v231
	v_cvt_pk_bf16_f32 v245, v232, v233
	v_mfma_f32_32x32x16_bf16 v[82:97], v[202:205], v[126:129], v[82:97]
	s_waitcnt lgkmcnt(0)
	v_mfma_f32_32x32x16_bf16 v[66:81], v[214:217], v[126:129], v[66:81]
	s_add_i32 s76, s77, 63
	s_cmp_le_i32 s76, s5
	s_cbranch_scc1 .Lff1b_z2
	v_cmp_le_i32_e32 vcc, v165, v195
	s_nop 8
	v_cndmask_b32_e32 v66, v155, v66, vcc
	v_cmp_lt_i32_e32 vcc, v163, v195
	s_nop 1
	v_cndmask_b32_e32 v83, v155, v83, vcc
	v_cmp_le_i32_e32 vcc, v163, v195
	s_nop 1
	v_cndmask_b32_e32 v82, v155, v82, vcc
	v_cmp_le_i32_e32 vcc, v166, v195
	s_nop 1
	v_cndmask_b32_e32 v67, v155, v67, vcc
	v_cmp_le_i32_e32 vcc, v167, v195
	s_nop 1
	v_cndmask_b32_e32 v84, v155, v84, vcc
	v_cmp_le_i32_e32 vcc, v168, v195
	s_nop 1
	v_cndmask_b32_e32 v68, v155, v68, vcc
	v_cmp_le_i32_e32 vcc, v169, v195
	s_nop 1
	v_cndmask_b32_e32 v85, v155, v85, vcc
	v_cmp_le_i32_e32 vcc, v170, v195
	s_nop 1
	v_cndmask_b32_e32 v69, v155, v69, vcc
	v_cmp_le_i32_e32 vcc, v171, v195
	s_nop 1
	v_cndmask_b32_e32 v86, v155, v86, vcc
	v_cmp_le_i32_e32 vcc, v172, v195
	s_nop 1
	v_cndmask_b32_e32 v70, v155, v70, vcc
	v_cmp_le_i32_e32 vcc, v173, v195
	s_nop 1
	v_cndmask_b32_e32 v87, v155, v87, vcc
	v_cmp_le_i32_e32 vcc, v174, v195
	s_nop 1
	v_cndmask_b32_e32 v71, v155, v71, vcc
	v_cmp_le_i32_e32 vcc, v175, v195
	s_nop 1
	v_cndmask_b32_e32 v88, v155, v88, vcc
	v_cmp_le_i32_e32 vcc, v176, v195
	s_nop 1
	v_cndmask_b32_e32 v72, v155, v72, vcc
	v_cmp_le_i32_e32 vcc, v177, v195
	s_nop 1
	v_cndmask_b32_e32 v89, v155, v89, vcc
	v_cmp_le_i32_e32 vcc, v178, v195
	s_nop 1
	v_cndmask_b32_e32 v73, v155, v73, vcc
	v_cmp_le_i32_e32 vcc, v179, v195
	s_nop 1
	v_cndmask_b32_e32 v90, v155, v90, vcc
	v_cmp_le_i32_e32 vcc, v180, v195
	s_nop 1
	v_cndmask_b32_e32 v74, v155, v74, vcc
	v_cmp_le_i32_e32 vcc, v181, v195
	s_nop 1
	v_cndmask_b32_e32 v91, v155, v91, vcc
	v_cmp_le_i32_e32 vcc, v182, v195
	s_nop 1
	v_cndmask_b32_e32 v75, v155, v75, vcc
	v_cmp_le_i32_e32 vcc, v183, v195
	s_nop 1
	v_cndmask_b32_e32 v92, v155, v92, vcc
	v_cmp_le_i32_e32 vcc, v184, v195
	s_nop 1
	v_cndmask_b32_e32 v76, v155, v76, vcc
	v_cmp_le_i32_e32 vcc, v185, v195
	s_nop 1
	v_cndmask_b32_e32 v93, v155, v93, vcc
	v_cmp_le_i32_e32 vcc, v186, v195
	s_nop 1
	v_cndmask_b32_e32 v77, v155, v77, vcc
	v_cmp_le_i32_e32 vcc, v187, v195
	s_nop 1
	v_cndmask_b32_e32 v94, v155, v94, vcc
	v_cmp_le_i32_e32 vcc, v188, v195
	s_nop 1
	v_cndmask_b32_e32 v78, v155, v78, vcc
	v_cmp_le_i32_e32 vcc, v189, v195
	s_nop 1
	v_cndmask_b32_e32 v95, v155, v95, vcc
	v_cmp_le_i32_e32 vcc, v190, v195
	s_nop 1
	v_cndmask_b32_e32 v79, v155, v79, vcc
	v_cmp_le_i32_e32 vcc, v191, v195
	s_nop 1
	v_cndmask_b32_e32 v96, v155, v96, vcc
	v_cmp_le_i32_e32 vcc, v192, v195
	s_nop 1
	v_cndmask_b32_e32 v80, v155, v80, vcc
	v_cmp_le_i32_e32 vcc, v193, v195
	s_nop 1
	v_cndmask_b32_e32 v97, v155, v97, vcc
	v_cmp_le_i32_e32 vcc, v194, v195
	s_nop 1
	v_cndmask_b32_e32 v81, v155, v81, vcc

.Lff1b_first:
	s_mul_i32 s34, s27, 0x4400
	v_add_u32_e32 v0, s34, v162
	ds_read_b128 v[198:201], v0
	ds_read_b128 v[202:205], v0 offset:32
	ds_read_b128 v[206:209], v0 offset:8704
	ds_read_b128 v[210:213], v0 offset:8736
	v_add_u32_e32 v78, s75, v149
	v_add_u32_e32 v66, 0x12800, v78
	v_add_u32_e32 v67, 0x12880, v78
	v_add_u32_e32 v70, 0x12820, v78
	v_add_u32_e32 v71, 0x128a0, v78
	v_add_u32_e32 v74, 0x12840, v78
	v_add_u32_e32 v75, 0x128c0, v78
	v_add_u32_e32 v79, 0x12860, v78
	v_add_u32_e32 v78, 0x128e0, v78
	ds_read_b128 v[82:85], v66
	ds_read_b128 v[66:69], v67
	ds_read_b128 v[86:89], v70
	ds_read_b128 v[70:73], v71
	ds_read_b128 v[90:93], v74
	ds_read_b128 v[74:77], v75
	ds_read_b128 v[94:97], v79
	ds_read_b128 v[78:81], v78
	s_waitcnt lgkmcnt(1)
	v_mfma_f32_32x32x16_bf16 v[82:97], v[198:201], v[98:101], v[82:97]
	s_waitcnt lgkmcnt(0)
	v_mfma_f32_32x32x16_bf16 v[66:81], v[206:209], v[98:101], v[66:81]
	v_mfma_f32_32x32x16_bf16 v[82:97], v[202:205], v[102:105], v[82:97]
	ds_read_b128 v[198:201], v0 offset:64
	ds_read_b128 v[202:205], v0 offset:96
	ds_read_b128 v[206:209], v0 offset:8768
	ds_read_b128 v[214:217], v0 offset:8800
	v_mfma_f32_32x32x16_bf16 v[66:81], v[210:213], v[102:105], v[66:81]
	s_waitcnt lgkmcnt(3)
	v_mfma_f32_32x32x16_bf16 v[82:97], v[198:201], v[106:109], v[82:97]
	s_waitcnt lgkmcnt(1)
	v_mfma_f32_32x32x16_bf16 v[66:81], v[206:209], v[106:109], v[66:81]
	v_mfma_f32_32x32x16_bf16 v[82:97], v[202:205], v[110:113], v[82:97]
	ds_read_b128 v[198:201], v0 offset:128
	ds_read_b128 v[202:205], v0 offset:160
	ds_read_b128 v[206:209], v0 offset:8832
	ds_read_b128 v[210:213], v0 offset:8864
	s_waitcnt lgkmcnt(4)
	v_mfma_f32_32x32x16_bf16 v[66:81], v[214:217], v[110:113], v[66:81]
	s_waitcnt lgkmcnt(3)
	v_mfma_f32_32x32x16_bf16 v[82:97], v[198:201], v[114:117], v[82:97]
	s_waitcnt lgkmcnt(1)
	v_mfma_f32_32x32x16_bf16 v[66:81], v[206:209], v[114:117], v[66:81]
	v_mfma_f32_32x32x16_bf16 v[82:97], v[202:205], v[118:121], v[82:97]
	ds_read_b128 v[198:201], v0 offset:192
	ds_read_b128 v[202:205], v0 offset:224
	ds_read_b128 v[206:209], v0 offset:8896
	ds_read_b128 v[214:217], v0 offset:8928
	s_waitcnt lgkmcnt(4)
	v_mfma_f32_32x32x16_bf16 v[66:81], v[210:213], v[118:121], v[66:81]
	s_waitcnt lgkmcnt(3)
	v_mfma_f32_32x32x16_bf16 v[82:97], v[198:201], v[122:125], v[82:97]
	s_waitcnt lgkmcnt(1)
	v_mfma_f32_32x32x16_bf16 v[66:81], v[206:209], v[122:125], v[66:81]
	v_mfma_f32_32x32x16_bf16 v[82:97], v[202:205], v[126:129], v[82:97]
	s_waitcnt lgkmcnt(0)
	v_mfma_f32_32x32x16_bf16 v[66:81], v[214:217], v[126:129], v[66:81]
	s_add_i32 s76, s77, 63
	s_cmp_le_i32 s76, s5
	s_cbranch_scc1 .Lff1b_m1
	v_cmp_le_i32_e32 vcc, v165, v195
	s_nop 8
	v_cndmask_b32_e32 v66, v155, v66, vcc
	v_cmp_lt_i32_e32 vcc, v163, v195
	s_nop 1
	v_cndmask_b32_e32 v83, v155, v83, vcc
	v_cmp_le_i32_e32 vcc, v163, v195
	s_nop 1
	v_cndmask_b32_e32 v82, v155, v82, vcc
	v_cmp_le_i32_e32 vcc, v166, v195
	s_nop 1
	v_cndmask_b32_e32 v67, v155, v67, vcc
	v_cmp_le_i32_e32 vcc, v167, v195
	s_nop 1
	v_cndmask_b32_e32 v84, v155, v84, vcc
	v_cmp_le_i32_e32 vcc, v168, v195
	s_nop 1
	v_cndmask_b32_e32 v68, v155, v68, vcc
	v_cmp_le_i32_e32 vcc, v169, v195
	s_nop 1
	v_cndmask_b32_e32 v85, v155, v85, vcc
	v_cmp_le_i32_e32 vcc, v170, v195
	s_nop 1
	v_cndmask_b32_e32 v69, v155, v69, vcc
	v_cmp_le_i32_e32 vcc, v171, v195
	s_nop 1
	v_cndmask_b32_e32 v86, v155, v86, vcc
	v_cmp_le_i32_e32 vcc, v172, v195
	s_nop 1
	v_cndmask_b32_e32 v70, v155, v70, vcc
	v_cmp_le_i32_e32 vcc, v173, v195
	s_nop 1
	v_cndmask_b32_e32 v87, v155, v87, vcc
	v_cmp_le_i32_e32 vcc, v174, v195
	s_nop 1
	v_cndmask_b32_e32 v71, v155, v71, vcc
	v_cmp_le_i32_e32 vcc, v175, v195
	s_nop 1
	v_cndmask_b32_e32 v88, v155, v88, vcc
	v_cmp_le_i32_e32 vcc, v176, v195
	s_nop 1
	v_cndmask_b32_e32 v72, v155, v72, vcc
	v_cmp_le_i32_e32 vcc, v177, v195
	s_nop 1
	v_cndmask_b32_e32 v89, v155, v89, vcc
	v_cmp_le_i32_e32 vcc, v178, v195
	s_nop 1
	v_cndmask_b32_e32 v73, v155, v73, vcc
	v_cmp_le_i32_e32 vcc, v179, v195
	s_nop 1
	v_cndmask_b32_e32 v90, v155, v90, vcc
	v_cmp_le_i32_e32 vcc, v180, v195
	s_nop 1
	v_cndmask_b32_e32 v74, v155, v74, vcc
	v_cmp_le_i32_e32 vcc, v181, v195
	s_nop 1
	v_cndmask_b32_e32 v91, v155, v91, vcc
	v_cmp_le_i32_e32 vcc, v182, v195
	s_nop 1
	v_cndmask_b32_e32 v75, v155, v75, vcc
	v_cmp_le_i32_e32 vcc, v183, v195
	s_nop 1
	v_cndmask_b32_e32 v92, v155, v92, vcc
	v_cmp_le_i32_e32 vcc, v184, v195
	s_nop 1
	v_cndmask_b32_e32 v76, v155, v76, vcc
	v_cmp_le_i32_e32 vcc, v185, v195
	s_nop 1
	v_cndmask_b32_e32 v93, v155, v93, vcc
	v_cmp_le_i32_e32 vcc, v186, v195
	s_nop 1
	v_cndmask_b32_e32 v77, v155, v77, vcc
	v_cmp_le_i32_e32 vcc, v187, v195
	s_nop 1
	v_cndmask_b32_e32 v94, v155, v94, vcc
	v_cmp_le_i32_e32 vcc, v188, v195
	s_nop 1
	v_cndmask_b32_e32 v78, v155, v78, vcc
	v_cmp_le_i32_e32 vcc, v189, v195
	s_nop 1
	v_cndmask_b32_e32 v95, v155, v95, vcc
	v_cmp_le_i32_e32 vcc, v190, v195
	s_nop 1
	v_cndmask_b32_e32 v79, v155, v79, vcc
	v_cmp_le_i32_e32 vcc, v191, v195
	s_nop 1
	v_cndmask_b32_e32 v96, v155, v96, vcc
	v_cmp_le_i32_e32 vcc, v192, v195
	s_nop 1
	v_cndmask_b32_e32 v80, v155, v80, vcc
	v_cmp_le_i32_e32 vcc, v193, v195
	s_nop 1
	v_cndmask_b32_e32 v97, v155, v97, vcc
	v_cmp_le_i32_e32 vcc, v194, v195
	s_nop 1
	v_cndmask_b32_e32 v81, v155, v81, vcc

.LBB0_654:
	s_setprio 0
	v_mov_b32_e32 v0, v196
	v_nop
	v_nop
	v_permlane32_swap_b32 v196, v0
	s_lshl_b32 s16, s16, 1
	v_add_f32_e32 v146, v196, v0
	v_ashrrev_i32_e32 v0, 31, v156
	v_lshrrev_b32_e32 v0, 28, v0
	v_add_u32_e32 v0, v156, v0
	s_waitcnt vmcnt(0)
	v_ashrrev_i32_e32 v144, 4, v0
	v_and_b32_e32 v0, -16, v0
	v_sub_u32_e32 v147, v156, v0
	v_lshlrev_b32_e32 v68, 3, v147
	v_ashrrev_i32_e32 v69, 31, v68
	v_add_u32_e32 v0, 64, v156
	v_lshlrev_b64 v[140:141], 1, v[68:69]
	v_ashrrev_i32_e32 v68, 31, v0
	v_lshrrev_b32_e32 v68, 28, v68
	v_ashrrev_i32_e32 v145, 31, v144
	v_add_u32_e32 v68, v0, v68
	v_lshl_add_u64 v[138:139], s[24:25], 0, v[144:145]
	v_ashrrev_i32_e32 v142, 4, v68
	v_lshlrev_b64 v[66:67], 14, v[138:139]
	v_and_b32_e32 v68, -16, v68
	v_ashrrev_i32_e32 v143, 31, v142
	v_lshl_add_u64 v[66:67], s[12:13], 0, v[66:67]
	v_sub_u32_e32 v145, v0, v68
	v_lshl_add_u64 v[132:133], s[24:25], 0, v[142:143]
	v_lshl_add_u64 v[66:67], v[66:67], 0, s[16:17]
	v_lshlrev_b64 v[68:69], 14, v[132:133]
	v_lshlrev_b32_e32 v70, 3, v145
	v_lshl_add_u64 v[66:67], v[66:67], 0, v[140:141]
	v_lshl_add_u64 v[68:69], s[12:13], 0, v[68:69]
	v_ashrrev_i32_e32 v71, 31, v70
	v_add_co_u32_e32 v66, vcc, s48, v66
	v_lshl_add_u64 v[68:69], v[68:69], 0, s[16:17]
	v_lshlrev_b64 v[134:135], 1, v[70:71]
	v_addc_co_u32_e32 v67, vcc, 0, v67, vcc
	v_lshl_add_u64 v[68:69], v[68:69], 0, v[134:135]
	v_add_co_u32_e32 v68, vcc, s48, v68
	v_add_u32_e32 v0, 0x80, v156
	s_nop 0
	v_addc_co_u32_e32 v69, vcc, 0, v69, vcc
	global_load_dwordx4 v[94:97], v[66:67], off
	global_load_dwordx4 v[90:93], v[68:69], off
	v_ashrrev_i32_e32 v66, 31, v0
	v_lshrrev_b32_e32 v66, 28, v66
	v_add_u32_e32 v66, v0, v66
	v_ashrrev_i32_e32 v136, 4, v66
	v_and_b32_e32 v66, -16, v66
	v_sub_u32_e32 v143, v0, v66
	v_lshlrev_b32_e32 v68, 3, v143
	v_ashrrev_i32_e32 v69, 31, v68
	v_add_u32_e32 v0, 0xc0, v156
	v_lshlrev_b64 v[128:129], 1, v[68:69]
	v_ashrrev_i32_e32 v68, 31, v0
	v_lshrrev_b32_e32 v68, 28, v68
	v_ashrrev_i32_e32 v137, 31, v136
	v_add_u32_e32 v68, v0, v68
	v_lshl_add_u64 v[126:127], s[24:25], 0, v[136:137]
	v_ashrrev_i32_e32 v130, 4, v68
	v_lshlrev_b64 v[66:67], 14, v[126:127]
	v_and_b32_e32 v68, -16, v68
	v_ashrrev_i32_e32 v131, 31, v130
	v_lshl_add_u64 v[66:67], s[12:13], 0, v[66:67]
	v_sub_u32_e32 v137, v0, v68
	v_lshl_add_u64 v[120:121], s[24:25], 0, v[130:131]
	v_lshl_add_u64 v[66:67], v[66:67], 0, s[16:17]
	v_lshlrev_b64 v[68:69], 14, v[120:121]
	v_lshlrev_b32_e32 v70, 3, v137
	v_lshl_add_u64 v[66:67], v[66:67], 0, v[128:129]
	v_lshl_add_u64 v[68:69], s[12:13], 0, v[68:69]
	v_ashrrev_i32_e32 v71, 31, v70
	v_add_co_u32_e32 v66, vcc, s48, v66
	v_lshl_add_u64 v[68:69], v[68:69], 0, s[16:17]
	v_lshlrev_b64 v[122:123], 1, v[70:71]
	v_addc_co_u32_e32 v67, vcc, 0, v67, vcc
	v_lshl_add_u64 v[68:69], v[68:69], 0, v[122:123]
	v_add_co_u32_e32 v68, vcc, s48, v68
	v_add_u32_e32 v0, 0x100, v156
	s_nop 0
	v_addc_co_u32_e32 v69, vcc, 0, v69, vcc
	global_load_dwordx4 v[86:89], v[66:67], off
	global_load_dwordx4 v[82:85], v[68:69], off
	v_ashrrev_i32_e32 v66, 31, v0
	v_lshrrev_b32_e32 v66, 28, v66
	v_add_u32_e32 v66, v0, v66
	v_ashrrev_i32_e32 v124, 4, v66
	v_and_b32_e32 v66, -16, v66
	v_sub_u32_e32 v131, v0, v66
	v_lshlrev_b32_e32 v68, 3, v131
	v_ashrrev_i32_e32 v69, 31, v68
	v_add_u32_e32 v0, 0x140, v156
	v_lshlrev_b64 v[116:117], 1, v[68:69]
	v_ashrrev_i32_e32 v68, 31, v0
	v_lshrrev_b32_e32 v68, 28, v68
	v_ashrrev_i32_e32 v125, 31, v124
	v_add_u32_e32 v68, v0, v68
	v_lshl_add_u64 v[114:115], s[24:25], 0, v[124:125]
	v_ashrrev_i32_e32 v118, 4, v68
	v_lshlrev_b64 v[66:67], 14, v[114:115]
	v_and_b32_e32 v68, -16, v68
	v_ashrrev_i32_e32 v119, 31, v118
	v_lshl_add_u64 v[66:67], s[12:13], 0, v[66:67]
	v_sub_u32_e32 v125, v0, v68
	v_lshl_add_u64 v[108:109], s[24:25], 0, v[118:119]
	v_lshl_add_u64 v[66:67], v[66:67], 0, s[16:17]
	v_lshlrev_b64 v[68:69], 14, v[108:109]
	v_lshlrev_b32_e32 v70, 3, v125
	v_lshl_add_u64 v[66:67], v[66:67], 0, v[116:117]
	v_lshl_add_u64 v[68:69], s[12:13], 0, v[68:69]
	v_ashrrev_i32_e32 v71, 31, v70
	v_add_co_u32_e32 v66, vcc, s48, v66
	v_lshl_add_u64 v[68:69], v[68:69], 0, s[16:17]
	v_lshlrev_b64 v[110:111], 1, v[70:71]
	v_addc_co_u32_e32 v67, vcc, 0, v67, vcc
	v_lshl_add_u64 v[68:69], v[68:69], 0, v[110:111]
	v_add_co_u32_e32 v68, vcc, s48, v68
	v_add_u32_e32 v0, 0x180, v156
	s_nop 0
	v_addc_co_u32_e32 v69, vcc, 0, v69, vcc
	global_load_dwordx4 v[78:81], v[66:67], off
	global_load_dwordx4 v[74:77], v[68:69], off
	v_ashrrev_i32_e32 v66, 31, v0
	v_lshrrev_b32_e32 v66, 28, v66
	v_add_u32_e32 v66, v0, v66
	v_ashrrev_i32_e32 v112, 4, v66
	v_and_b32_e32 v66, -16, v66
	v_sub_u32_e32 v119, v0, v66
	v_lshlrev_b32_e32 v68, 3, v119
	v_ashrrev_i32_e32 v69, 31, v68
	v_add_u32_e32 v0, 0x1c0, v156
	v_lshlrev_b64 v[104:105], 1, v[68:69]
	v_ashrrev_i32_e32 v68, 31, v0
	v_lshrrev_b32_e32 v68, 28, v68
	v_ashrrev_i32_e32 v113, 31, v112
	v_add_u32_e32 v68, v0, v68
	v_lshl_add_u64 v[102:103], s[24:25], 0, v[112:113]
	v_ashrrev_i32_e32 v106, 4, v68
	v_lshlrev_b64 v[66:67], 14, v[102:103]
	v_and_b32_e32 v68, -16, v68
	v_ashrrev_i32_e32 v107, 31, v106
	s_and_b32 s0, s49, 7
	v_lshl_add_u64 v[66:67], s[12:13], 0, v[66:67]
	v_sub_u32_e32 v0, v0, v68
	v_lshl_add_u64 v[98:99], s[24:25], 0, v[106:107]
	s_lshl_b32 s7, s0, 8
	s_lshl_b32 s6, s0, 10
	v_lshl_add_u64 v[66:67], v[66:67], 0, s[16:17]
	v_lshlrev_b64 v[68:69], 14, v[98:99]
	v_lshlrev_b32_e32 v70, 3, v0
	v_div_scale_f32 v107, s[0:1], v146, v146, 1.0
	v_lshl_add_u64 v[66:67], v[66:67], 0, v[104:105]
	v_lshl_add_u64 v[68:69], s[12:13], 0, v[68:69]
	v_ashrrev_i32_e32 v71, 31, v70
	v_rcp_f32_e32 v113, v107
	v_add_co_u32_e32 v66, vcc, s48, v66
	v_lshl_add_u64 v[68:69], v[68:69], 0, s[16:17]
	v_lshlrev_b64 v[100:101], 1, v[70:71]
	v_addc_co_u32_e32 v67, vcc, 0, v67, vcc
	v_lshl_add_u64 v[68:69], v[68:69], 0, v[100:101]
	v_add_co_u32_e32 v68, vcc, s48, v68
	v_fma_f32 v148, -v107, v113, 1.0
	s_nop 0
	v_addc_co_u32_e32 v69, vcc, 0, v69, vcc
	v_fmac_f32_e32 v113, v148, v113
	v_div_scale_f32 v148, vcc, 1.0, v146, 1.0
	v_mul_f32_e32 v149, v148, v113
	v_fma_f32 v150, -v107, v149, v148
	v_fmac_f32_e32 v149, v150, v113
	v_fma_f32 v107, -v107, v149, v148
	v_div_fmas_f32 v107, v107, v113, v149
	v_div_fixup_f32 v146, v107, v146, 1.0
	v_pk_mul_f32 v[50:51], v[50:51], v[146:147] op_sel_hi:[1,0]
	v_pk_mul_f32 v[52:53], v[52:53], v[146:147] op_sel_hi:[1,0]
	s_mulk_i32 s33, 0x110
	v_and_b32_e32 v107, 31, v156
	v_cvt_pk_bf16_f32 v50, v50, v51
	v_cvt_pk_bf16_f32 v51, v52, v53
	v_ashrrev_i32_e32 v52, 2, v156
	v_pk_mul_f32 v[2:3], v[2:3], v[146:147] op_sel_hi:[1,0]
	v_pk_mul_f32 v[4:5], v[4:5], v[146:147] op_sel_hi:[1,0]
	s_add_i32 s4, s33, 0
	v_mul_u32_u24_e32 v107, 0x110, v107
	v_and_b32_e32 v52, -8, v52
	v_cvt_pk_bf16_f32 v2, v2, v3
	v_cvt_pk_bf16_f32 v3, v4, v5
	v_pk_mul_f32 v[4:5], v[6:7], v[146:147] op_sel_hi:[1,0]
	v_pk_mul_f32 v[6:7], v[8:9], v[146:147] op_sel_hi:[1,0]
	v_add3_u32 v107, s4, v107, v52
	v_cvt_pk_bf16_f32 v4, v4, v5
	v_cvt_pk_bf16_f32 v5, v6, v7
	global_load_dwordx4 v[70:73], v[66:67], off
	s_nop 0
	global_load_dwordx4 v[66:69], v[68:69], off
	v_pk_mul_f32 v[34:35], v[34:35], v[146:147] op_sel_hi:[1,0]
	v_pk_mul_f32 v[36:37], v[36:37], v[146:147] op_sel_hi:[1,0]
	v_pk_mul_f32 v[18:19], v[18:19], v[146:147] op_sel_hi:[1,0]
	v_pk_mul_f32 v[20:21], v[20:21], v[146:147] op_sel_hi:[1,0]
	ds_write2_b64 v107, v[2:3], v[4:5] offset0:24 offset1:26
	v_pk_mul_f32 v[2:3], v[10:11], v[146:147] op_sel_hi:[1,0]
	v_pk_mul_f32 v[4:5], v[12:13], v[146:147] op_sel_hi:[1,0]
	v_pk_mul_f32 v[52:53], v[54:55], v[146:147] op_sel_hi:[1,0]
	v_pk_mul_f32 v[54:55], v[56:57], v[146:147] op_sel_hi:[1,0]
	v_cvt_pk_bf16_f32 v34, v34, v35
	v_cvt_pk_bf16_f32 v35, v36, v37
	v_pk_mul_f32 v[36:37], v[38:39], v[146:147] op_sel_hi:[1,0]
	v_pk_mul_f32 v[38:39], v[40:41], v[146:147] op_sel_hi:[1,0]
	v_cvt_pk_bf16_f32 v18, v18, v19
	v_cvt_pk_bf16_f32 v19, v20, v21
	v_pk_mul_f32 v[20:21], v[22:23], v[146:147] op_sel_hi:[1,0]
	v_pk_mul_f32 v[22:23], v[24:25], v[146:147] op_sel_hi:[1,0]
	v_cvt_pk_bf16_f32 v2, v2, v3
	v_cvt_pk_bf16_f32 v3, v4, v5
	v_pk_mul_f32 v[4:5], v[14:15], v[146:147] op_sel_hi:[1,0]
	v_pk_mul_f32 v[6:7], v[16:17], v[146:147] op_sel_hi:[1,0]
	v_cvt_pk_bf16_f32 v52, v52, v53
	v_cvt_pk_bf16_f32 v53, v54, v55
	v_cvt_pk_bf16_f32 v36, v36, v37
	v_cvt_pk_bf16_f32 v37, v38, v39
	v_cvt_pk_bf16_f32 v20, v20, v21
	v_cvt_pk_bf16_f32 v21, v22, v23
	v_cvt_pk_bf16_f32 v4, v4, v5
	v_cvt_pk_bf16_f32 v5, v6, v7
	ds_write2_b64 v107, v[50:51], v[52:53] offset1:2
	v_pk_mul_f32 v[50:51], v[58:59], v[146:147] op_sel_hi:[1,0]
	v_pk_mul_f32 v[52:53], v[60:61], v[146:147] op_sel_hi:[1,0]
	ds_write2_b64 v107, v[34:35], v[36:37] offset0:8 offset1:10
	v_pk_mul_f32 v[34:35], v[42:43], v[146:147] op_sel_hi:[1,0]
	v_pk_mul_f32 v[36:37], v[44:45], v[146:147] op_sel_hi:[1,0]
	ds_write2_b64 v107, v[18:19], v[20:21] offset0:16 offset1:18
	v_pk_mul_f32 v[18:19], v[26:27], v[146:147] op_sel_hi:[1,0]
	v_pk_mul_f32 v[20:21], v[28:29], v[146:147] op_sel_hi:[1,0]
	ds_write2_b64 v107, v[2:3], v[4:5] offset0:28 offset1:30
	v_mul_lo_u32 v2, v144, s45
	v_lshlrev_b32_e32 v3, 4, v147
	s_waitcnt vmcnt(7)
	v_lshlrev_b32_e32 v10, 16, v94
	v_cvt_pk_bf16_f32 v50, v50, v51
	v_cvt_pk_bf16_f32 v51, v52, v53
	v_pk_mul_f32 v[52:53], v[62:63], v[146:147] op_sel_hi:[1,0]
	v_pk_mul_f32 v[54:55], v[64:65], v[146:147] op_sel_hi:[1,0]
	v_cvt_pk_bf16_f32 v34, v34, v35
	v_cvt_pk_bf16_f32 v35, v36, v37
	v_pk_mul_f32 v[36:37], v[46:47], v[146:147] op_sel_hi:[1,0]
	v_pk_mul_f32 v[38:39], v[48:49], v[146:147] op_sel_hi:[1,0]
	v_cvt_pk_bf16_f32 v18, v18, v19
	v_cvt_pk_bf16_f32 v19, v20, v21
	v_pk_mul_f32 v[20:21], v[30:31], v[146:147] op_sel_hi:[1,0]
	v_pk_mul_f32 v[22:23], v[32:33], v[146:147] op_sel_hi:[1,0]
	v_add3_u32 v2, s4, v2, v3
	v_and_b32_e32 v13, 0xffff0000, v94
	v_mul_f32_e32 v3, 0xbfb8aa3b, v10
	v_cvt_pk_bf16_f32 v52, v52, v53
	v_cvt_pk_bf16_f32 v53, v54, v55
	v_cvt_pk_bf16_f32 v36, v36, v37
	v_cvt_pk_bf16_f32 v37, v38, v39
	v_cvt_pk_bf16_f32 v20, v20, v21
	v_cvt_pk_bf16_f32 v21, v22, v23
	v_exp_f32_e32 v6, v3
	v_mul_f32_e32 v3, 0xbfb8aa3b, v13
	ds_write2_b64 v107, v[50:51], v[52:53] offset0:4 offset1:6
	ds_write2_b64 v107, v[34:35], v[36:37] offset0:12 offset1:14
	ds_write2_b64 v107, v[18:19], v[20:21] offset0:20 offset1:22
	v_exp_f32_e32 v7, v3
	s_waitcnt lgkmcnt(0)
	ds_read_b128 v[2:5], v2
	v_add_f32_e32 v6, 1.0, v6
	v_rcp_f32_e32 v14, v6
	v_add_f32_e32 v6, 1.0, v7
	v_rcp_f32_e32 v15, v6
	v_mul_lo_u32 v6, v142, s45
	v_lshlrev_b32_e32 v7, 4, v145
	v_add3_u32 v6, s4, v6, v7
	ds_read_b128 v[6:9], v6
	s_waitcnt lgkmcnt(1)
	v_and_b32_e32 v11, 0xffff0000, v2
	v_lshlrev_b32_e32 v12, 16, v2
	v_pk_mul_f32 v[10:11], v[12:13], v[10:11]
	v_lshlrev_b32_e32 v12, 16, v95
	v_pk_mul_f32 v[10:11], v[14:15], v[10:11]
	v_and_b32_e32 v15, 0xffff0000, v95
	v_mul_f32_e32 v2, 0xbfb8aa3b, v12
	v_exp_f32_e32 v13, v2
	v_mul_f32_e32 v2, 0xbfb8aa3b, v15
	v_exp_f32_e32 v14, v2
	v_cvt_pk_bf16_f32 v2, v10, v11
	v_add_f32_e32 v10, 1.0, v13
	v_rcp_f32_e32 v10, v10
	v_add_f32_e32 v11, 1.0, v14
	v_rcp_f32_e32 v11, v11
	v_and_b32_e32 v13, 0xffff0000, v3
	v_lshlrev_b32_e32 v14, 16, v3
	v_pk_mul_f32 v[12:13], v[14:15], v[12:13]
	v_and_b32_e32 v15, 0xffff0000, v96
	v_pk_mul_f32 v[10:11], v[10:11], v[12:13]
	v_lshlrev_b32_e32 v12, 16, v96
	v_mul_f32_e32 v3, 0xbfb8aa3b, v12
	v_exp_f32_e32 v13, v3
	v_mul_f32_e32 v3, 0xbfb8aa3b, v15
	v_exp_f32_e32 v14, v3
	v_cvt_pk_bf16_f32 v3, v10, v11
	v_add_f32_e32 v10, 1.0, v13
	v_rcp_f32_e32 v10, v10
	v_add_f32_e32 v11, 1.0, v14
	v_rcp_f32_e32 v11, v11
	v_and_b32_e32 v13, 0xffff0000, v4
	v_lshlrev_b32_e32 v14, 16, v4
	v_pk_mul_f32 v[12:13], v[14:15], v[12:13]
	v_and_b32_e32 v15, 0xffff0000, v97
	v_pk_mul_f32 v[10:11], v[10:11], v[12:13]
	v_lshlrev_b32_e32 v12, 16, v97
	v_mul_f32_e32 v4, 0xbfb8aa3b, v12
	v_exp_f32_e32 v13, v4
	v_mul_f32_e32 v4, 0xbfb8aa3b, v15
	v_exp_f32_e32 v14, v4
	v_cvt_pk_bf16_f32 v4, v10, v11
	v_add_f32_e32 v10, 1.0, v13
	v_rcp_f32_e32 v10, v10
	v_add_f32_e32 v11, 1.0, v14
	v_rcp_f32_e32 v11, v11
	v_and_b32_e32 v13, 0xffff0000, v5
	v_lshlrev_b32_e32 v14, 16, v5
	v_pk_mul_f32 v[12:13], v[14:15], v[12:13]
	s_waitcnt vmcnt(6)
	v_and_b32_e32 v15, 0xffff0000, v90
	v_pk_mul_f32 v[10:11], v[10:11], v[12:13]
	v_lshlrev_b32_e32 v12, 16, v90
	s_addk_i32 s6, 0x400
	v_mul_f32_e32 v13, 0xbfb8aa3b, v12
	v_mul_f32_e32 v14, 0xbfb8aa3b, v15
	s_add_u32 s0, s36, s16
	v_exp_f32_e32 v13, v13
	v_exp_f32_e32 v14, v14
	s_addc_u32 s1, s37, 0
	v_cvt_pk_bf16_f32 v5, v10, v11
	v_lshlrev_b64 v[10:11], 12, v[138:139]
	v_lshl_add_u64 v[10:11], s[0:1], 0, v[10:11]
	v_lshl_add_u64 v[10:11], v[10:11], 0, v[140:141]
	global_store_dwordx4 v[10:11], v[2:5], off
	v_and_b32_e32 v11, 0xffff0000, v91
	s_waitcnt lgkmcnt(0)
	v_lshlrev_b32_e32 v10, 16, v7
	v_add_f32_e32 v2, 1.0, v13
	v_add_f32_e32 v3, 1.0, v14
	v_rcp_f32_e32 v2, v2
	v_rcp_f32_e32 v3, v3
	v_and_b32_e32 v13, 0xffff0000, v6
	v_lshlrev_b32_e32 v14, 16, v6
	v_pk_mul_f32 v[4:5], v[14:15], v[12:13]
	v_mul_f32_e32 v6, 0xbfb8aa3b, v11
	v_pk_mul_f32 v[2:3], v[2:3], v[4:5]
	v_lshlrev_b32_e32 v4, 16, v91
	v_mul_f32_e32 v5, 0xbfb8aa3b, v4
	v_exp_f32_e32 v5, v5
	v_exp_f32_e32 v6, v6
	v_cvt_pk_bf16_f32 v2, v2, v3
	v_lshlrev_b32_e32 v0, 4, v0
	v_add_f32_e32 v3, 1.0, v5
	v_rcp_f32_e32 v12, v3
	v_add_f32_e32 v3, 1.0, v6
	v_and_b32_e32 v5, 0xffff0000, v7
	v_lshlrev_b32_e32 v6, 16, v92
	v_rcp_f32_e32 v13, v3
	v_pk_mul_f32 v[4:5], v[10:11], v[4:5]
	v_and_b32_e32 v11, 0xffff0000, v92
	v_mul_f32_e32 v3, 0xbfb8aa3b, v6
	v_exp_f32_e32 v7, v3
	v_mul_f32_e32 v3, 0xbfb8aa3b, v11
	v_exp_f32_e32 v10, v3
	v_pk_mul_f32 v[4:5], v[12:13], v[4:5]
	v_mov_b32_e32 v28, v255
	v_cvt_pk_bf16_f32 v3, v4, v5
	v_add_f32_e32 v4, 1.0, v7
	v_add_f32_e32 v5, 1.0, v10
	v_rcp_f32_e32 v4, v4
	v_rcp_f32_e32 v5, v5
	v_and_b32_e32 v7, 0xffff0000, v8
	v_lshlrev_b32_e32 v10, 16, v8
	v_pk_mul_f32 v[6:7], v[10:11], v[6:7]
	v_and_b32_e32 v11, 0xffff0000, v93
	v_pk_mul_f32 v[4:5], v[4:5], v[6:7]
	v_lshlrev_b32_e32 v6, 16, v93
	v_mul_f32_e32 v7, 0xbfb8aa3b, v6
	v_exp_f32_e32 v7, v7
	v_mul_f32_e32 v8, 0xbfb8aa3b, v11
	v_exp_f32_e32 v8, v8
	v_cvt_pk_bf16_f32 v4, v4, v5
	v_add_f32_e32 v5, 1.0, v7
	v_rcp_f32_e32 v12, v5
	v_add_f32_e32 v5, 1.0, v8
	v_rcp_f32_e32 v13, v5
	v_and_b32_e32 v7, 0xffff0000, v9
	v_lshlrev_b32_e32 v10, 16, v9
	v_pk_mul_f32 v[6:7], v[10:11], v[6:7]
	s_waitcnt vmcnt(6)
	v_lshlrev_b32_e32 v10, 16, v86
	v_pk_mul_f32 v[6:7], v[12:13], v[6:7]
	v_and_b32_e32 v13, 0xffff0000, v86
	v_cvt_pk_bf16_f32 v5, v6, v7
	v_lshlrev_b64 v[6:7], 12, v[132:133]
	v_lshl_add_u64 v[6:7], s[0:1], 0, v[6:7]
	v_lshl_add_u64 v[6:7], v[6:7], 0, v[134:135]
	global_store_dwordx4 v[6:7], v[2:5], off
	s_lshl_b32 s27, s50, 8
	s_or_b32 s5, s22, s27
	v_mul_lo_u32 v2, v136, s45
	v_lshlrev_b32_e32 v3, 4, v143
	v_add3_u32 v2, s4, v2, v3
	v_mul_f32_e32 v3, 0xbfb8aa3b, v10
	v_exp_f32_e32 v6, v3
	v_mul_f32_e32 v3, 0xbfb8aa3b, v13
	v_exp_f32_e32 v7, v3
	ds_read_b128 v[2:5], v2
	v_add_f32_e32 v6, 1.0, v6
	v_rcp_f32_e32 v14, v6
	v_add_f32_e32 v6, 1.0, v7
	v_rcp_f32_e32 v15, v6
	v_mul_lo_u32 v6, v130, s45
	v_lshlrev_b32_e32 v7, 4, v137
	v_add3_u32 v6, s4, v6, v7
	ds_read_b128 v[6:9], v6
	s_waitcnt lgkmcnt(1)
	v_and_b32_e32 v11, 0xffff0000, v2
	v_lshlrev_b32_e32 v12, 16, v2
	v_pk_mul_f32 v[10:11], v[12:13], v[10:11]
	v_lshlrev_b32_e32 v12, 16, v87
	v_pk_mul_f32 v[10:11], v[14:15], v[10:11]
	v_and_b32_e32 v15, 0xffff0000, v87
	v_mul_f32_e32 v2, 0xbfb8aa3b, v12
	v_exp_f32_e32 v13, v2
	v_mul_f32_e32 v2, 0xbfb8aa3b, v15
	v_exp_f32_e32 v14, v2
	v_cvt_pk_bf16_f32 v2, v10, v11
	v_add_f32_e32 v10, 1.0, v13
	v_rcp_f32_e32 v10, v10
	v_add_f32_e32 v11, 1.0, v14
	v_rcp_f32_e32 v11, v11
	v_and_b32_e32 v13, 0xffff0000, v3
	v_lshlrev_b32_e32 v14, 16, v3
	v_pk_mul_f32 v[12:13], v[14:15], v[12:13]
	v_and_b32_e32 v15, 0xffff0000, v88
	v_pk_mul_f32 v[10:11], v[10:11], v[12:13]
	v_lshlrev_b32_e32 v12, 16, v88
	v_mul_f32_e32 v3, 0xbfb8aa3b, v12
	v_exp_f32_e32 v13, v3
	v_mul_f32_e32 v3, 0xbfb8aa3b, v15
	v_exp_f32_e32 v14, v3
	v_cvt_pk_bf16_f32 v3, v10, v11
	v_add_f32_e32 v10, 1.0, v13
	v_rcp_f32_e32 v10, v10
	v_add_f32_e32 v11, 1.0, v14
	v_rcp_f32_e32 v11, v11
	v_and_b32_e32 v13, 0xffff0000, v4
	v_lshlrev_b32_e32 v14, 16, v4
	v_pk_mul_f32 v[12:13], v[14:15], v[12:13]
	v_and_b32_e32 v15, 0xffff0000, v89
	v_pk_mul_f32 v[10:11], v[10:11], v[12:13]
	v_lshlrev_b32_e32 v12, 16, v89
	v_mul_f32_e32 v4, 0xbfb8aa3b, v12
	v_exp_f32_e32 v13, v4
	v_mul_f32_e32 v4, 0xbfb8aa3b, v15
	v_exp_f32_e32 v14, v4
	v_cvt_pk_bf16_f32 v4, v10, v11
	v_add_f32_e32 v10, 1.0, v13
	v_rcp_f32_e32 v10, v10
	v_add_f32_e32 v11, 1.0, v14
	v_rcp_f32_e32 v11, v11
	v_and_b32_e32 v13, 0xffff0000, v5
	v_lshlrev_b32_e32 v14, 16, v5
	v_pk_mul_f32 v[12:13], v[14:15], v[12:13]
	s_waitcnt vmcnt(6)
	v_and_b32_e32 v15, 0xffff0000, v82
	v_pk_mul_f32 v[10:11], v[10:11], v[12:13]
	v_lshlrev_b32_e32 v12, 16, v82
	v_mul_f32_e32 v13, 0xbfb8aa3b, v12
	v_mul_f32_e32 v14, 0xbfb8aa3b, v15
	v_exp_f32_e32 v13, v13
	v_exp_f32_e32 v14, v14
	v_cvt_pk_bf16_f32 v5, v10, v11
	v_lshlrev_b64 v[10:11], 12, v[126:127]
	v_lshl_add_u64 v[10:11], s[0:1], 0, v[10:11]
	v_lshl_add_u64 v[10:11], v[10:11], 0, v[128:129]
	global_store_dwordx4 v[10:11], v[2:5], off
	v_and_b32_e32 v11, 0xffff0000, v83
	s_waitcnt lgkmcnt(0)
	v_lshlrev_b32_e32 v10, 16, v7
	v_add_f32_e32 v2, 1.0, v13
	v_add_f32_e32 v3, 1.0, v14
	v_rcp_f32_e32 v2, v2
	v_rcp_f32_e32 v3, v3
	v_and_b32_e32 v13, 0xffff0000, v6
	v_lshlrev_b32_e32 v14, 16, v6
	v_pk_mul_f32 v[4:5], v[14:15], v[12:13]
	v_mul_f32_e32 v6, 0xbfb8aa3b, v11
	v_pk_mul_f32 v[2:3], v[2:3], v[4:5]
	v_lshlrev_b32_e32 v4, 16, v83
	v_mul_f32_e32 v5, 0xbfb8aa3b, v4
	v_exp_f32_e32 v5, v5
	v_exp_f32_e32 v6, v6
	v_cvt_pk_bf16_f32 v2, v2, v3
	s_lshl_b32 s33, s50, 2
	v_add_f32_e32 v3, 1.0, v5
	v_rcp_f32_e32 v12, v3
	v_add_f32_e32 v3, 1.0, v6
	v_and_b32_e32 v5, 0xffff0000, v7
	v_lshlrev_b32_e32 v6, 16, v84
	v_rcp_f32_e32 v13, v3
	v_pk_mul_f32 v[4:5], v[10:11], v[4:5]
	v_and_b32_e32 v11, 0xffff0000, v84
	v_mul_f32_e32 v3, 0xbfb8aa3b, v6
	v_exp_f32_e32 v7, v3
	v_mul_f32_e32 v3, 0xbfb8aa3b, v11
	v_exp_f32_e32 v10, v3
	v_pk_mul_f32 v[4:5], v[12:13], v[4:5]
	s_mov_b32 s24, 0
	v_cvt_pk_bf16_f32 v3, v4, v5
	v_add_f32_e32 v4, 1.0, v7
	v_add_f32_e32 v5, 1.0, v10
	v_rcp_f32_e32 v4, v4
	v_rcp_f32_e32 v5, v5
	v_and_b32_e32 v7, 0xffff0000, v8
	v_lshlrev_b32_e32 v10, 16, v8
	v_pk_mul_f32 v[6:7], v[10:11], v[6:7]
	v_and_b32_e32 v11, 0xffff0000, v85
	v_pk_mul_f32 v[4:5], v[4:5], v[6:7]
	v_lshlrev_b32_e32 v6, 16, v85
	v_mul_f32_e32 v7, 0xbfb8aa3b, v6
	v_exp_f32_e32 v7, v7
	v_mul_f32_e32 v8, 0xbfb8aa3b, v11
	v_exp_f32_e32 v8, v8
	v_cvt_pk_bf16_f32 v4, v4, v5
	v_add_f32_e32 v5, 1.0, v7
	v_rcp_f32_e32 v12, v5
	v_add_f32_e32 v5, 1.0, v8
	v_rcp_f32_e32 v13, v5
	v_and_b32_e32 v7, 0xffff0000, v9
	v_lshlrev_b32_e32 v10, 16, v9
	v_pk_mul_f32 v[6:7], v[10:11], v[6:7]
	s_waitcnt vmcnt(6)
	v_lshlrev_b32_e32 v10, 16, v78
	v_pk_mul_f32 v[6:7], v[12:13], v[6:7]
	v_and_b32_e32 v13, 0xffff0000, v78
	v_cvt_pk_bf16_f32 v5, v6, v7
	v_lshlrev_b64 v[6:7], 12, v[120:121]
	v_lshl_add_u64 v[6:7], s[0:1], 0, v[6:7]
	v_lshl_add_u64 v[6:7], v[6:7], 0, v[122:123]
	global_store_dwordx4 v[6:7], v[2:5], off
	s_mov_b32 s25, 2
	s_mov_b32 s26, 63
	v_mul_lo_u32 v2, v124, s45
	v_lshlrev_b32_e32 v3, 4, v131
	v_add3_u32 v2, s4, v2, v3
	v_mul_f32_e32 v3, 0xbfb8aa3b, v10
	v_exp_f32_e32 v6, v3
	v_mul_f32_e32 v3, 0xbfb8aa3b, v13
	v_exp_f32_e32 v7, v3
	ds_read_b128 v[2:5], v2
	v_add_f32_e32 v6, 1.0, v6
	v_rcp_f32_e32 v14, v6
	v_add_f32_e32 v6, 1.0, v7
	v_rcp_f32_e32 v15, v6
	v_mul_lo_u32 v6, v118, s45
	v_lshlrev_b32_e32 v7, 4, v125
	v_add3_u32 v6, s4, v6, v7
	ds_read_b128 v[6:9], v6
	s_waitcnt lgkmcnt(1)
	v_and_b32_e32 v11, 0xffff0000, v2
	v_lshlrev_b32_e32 v12, 16, v2
	v_pk_mul_f32 v[10:11], v[12:13], v[10:11]
	v_lshlrev_b32_e32 v12, 16, v79
	v_pk_mul_f32 v[10:11], v[14:15], v[10:11]
	v_and_b32_e32 v15, 0xffff0000, v79
	v_mul_f32_e32 v2, 0xbfb8aa3b, v12
	v_exp_f32_e32 v13, v2
	v_mul_f32_e32 v2, 0xbfb8aa3b, v15
	v_exp_f32_e32 v14, v2
	v_cvt_pk_bf16_f32 v2, v10, v11
	v_add_f32_e32 v10, 1.0, v13
	v_rcp_f32_e32 v10, v10
	v_add_f32_e32 v11, 1.0, v14
	v_rcp_f32_e32 v11, v11
	v_and_b32_e32 v13, 0xffff0000, v3
	v_lshlrev_b32_e32 v14, 16, v3
	v_pk_mul_f32 v[12:13], v[14:15], v[12:13]
	v_and_b32_e32 v15, 0xffff0000, v80
	v_pk_mul_f32 v[10:11], v[10:11], v[12:13]
	v_lshlrev_b32_e32 v12, 16, v80
	v_mul_f32_e32 v3, 0xbfb8aa3b, v12
	v_exp_f32_e32 v13, v3
	v_mul_f32_e32 v3, 0xbfb8aa3b, v15
	v_exp_f32_e32 v14, v3
	v_cvt_pk_bf16_f32 v3, v10, v11
	v_add_f32_e32 v10, 1.0, v13
	v_rcp_f32_e32 v10, v10
	v_add_f32_e32 v11, 1.0, v14
	v_rcp_f32_e32 v11, v11
	v_and_b32_e32 v13, 0xffff0000, v4
	v_lshlrev_b32_e32 v14, 16, v4
	v_pk_mul_f32 v[12:13], v[14:15], v[12:13]
	v_and_b32_e32 v15, 0xffff0000, v81
	v_pk_mul_f32 v[10:11], v[10:11], v[12:13]
	v_lshlrev_b32_e32 v12, 16, v81
	v_mul_f32_e32 v4, 0xbfb8aa3b, v12
	v_exp_f32_e32 v13, v4
	v_mul_f32_e32 v4, 0xbfb8aa3b, v15
	v_exp_f32_e32 v14, v4
	v_cvt_pk_bf16_f32 v4, v10, v11
	v_add_f32_e32 v10, 1.0, v13
	v_rcp_f32_e32 v10, v10
	v_add_f32_e32 v11, 1.0, v14
	v_rcp_f32_e32 v11, v11
	v_and_b32_e32 v13, 0xffff0000, v5
	v_lshlrev_b32_e32 v14, 16, v5
	v_pk_mul_f32 v[12:13], v[14:15], v[12:13]
	s_waitcnt vmcnt(6)
	v_and_b32_e32 v15, 0xffff0000, v74
	v_pk_mul_f32 v[10:11], v[10:11], v[12:13]
	v_lshlrev_b32_e32 v12, 16, v74
	v_mul_f32_e32 v13, 0xbfb8aa3b, v12
	v_mul_f32_e32 v14, 0xbfb8aa3b, v15
	v_exp_f32_e32 v13, v13
	v_exp_f32_e32 v14, v14
	v_cvt_pk_bf16_f32 v5, v10, v11
	v_lshlrev_b64 v[10:11], 12, v[114:115]
	v_lshl_add_u64 v[10:11], s[0:1], 0, v[10:11]
	v_lshl_add_u64 v[10:11], v[10:11], 0, v[116:117]
	global_store_dwordx4 v[10:11], v[2:5], off
	v_and_b32_e32 v11, 0xffff0000, v75
	s_waitcnt lgkmcnt(0)
	v_lshlrev_b32_e32 v10, 16, v7
	v_add_f32_e32 v2, 1.0, v13
	v_add_f32_e32 v3, 1.0, v14
	v_rcp_f32_e32 v2, v2
	v_rcp_f32_e32 v3, v3
	v_and_b32_e32 v13, 0xffff0000, v6
	v_lshlrev_b32_e32 v14, 16, v6
	v_pk_mul_f32 v[4:5], v[14:15], v[12:13]
	v_mul_f32_e32 v6, 0xbfb8aa3b, v11
	v_pk_mul_f32 v[2:3], v[2:3], v[4:5]
	v_lshlrev_b32_e32 v4, 16, v75
	v_mul_f32_e32 v5, 0xbfb8aa3b, v4
	v_exp_f32_e32 v5, v5
	v_exp_f32_e32 v6, v6
	v_cvt_pk_bf16_f32 v2, v2, v3
	v_mov_b32_e32 v196, 0
	v_add_f32_e32 v3, 1.0, v5
	v_rcp_f32_e32 v12, v3
	v_add_f32_e32 v3, 1.0, v6
	v_and_b32_e32 v5, 0xffff0000, v7
	v_lshlrev_b32_e32 v6, 16, v76
	v_rcp_f32_e32 v13, v3
	v_pk_mul_f32 v[4:5], v[10:11], v[4:5]
	v_and_b32_e32 v11, 0xffff0000, v76
	v_mul_f32_e32 v3, 0xbfb8aa3b, v6
	v_exp_f32_e32 v7, v3
	v_mul_f32_e32 v3, 0xbfb8aa3b, v11
	v_exp_f32_e32 v10, v3
	v_pk_mul_f32 v[4:5], v[12:13], v[4:5]
	v_mov_b32_e32 v197, 0xf149f2ca
	v_cvt_pk_bf16_f32 v3, v4, v5
	v_add_f32_e32 v4, 1.0, v7
	v_add_f32_e32 v5, 1.0, v10
	v_rcp_f32_e32 v4, v4
	v_rcp_f32_e32 v5, v5
	v_and_b32_e32 v7, 0xffff0000, v8
	v_lshlrev_b32_e32 v10, 16, v8
	v_pk_mul_f32 v[6:7], v[10:11], v[6:7]
	v_and_b32_e32 v11, 0xffff0000, v77
	v_pk_mul_f32 v[4:5], v[4:5], v[6:7]
	v_lshlrev_b32_e32 v6, 16, v77
	v_mul_f32_e32 v7, 0xbfb8aa3b, v6
	v_exp_f32_e32 v7, v7
	v_mul_f32_e32 v8, 0xbfb8aa3b, v11
	v_exp_f32_e32 v8, v8
	v_cvt_pk_bf16_f32 v4, v4, v5
	v_add_f32_e32 v5, 1.0, v7
	v_rcp_f32_e32 v12, v5
	v_add_f32_e32 v5, 1.0, v8
	v_rcp_f32_e32 v13, v5
	v_and_b32_e32 v7, 0xffff0000, v9
	v_lshlrev_b32_e32 v10, 16, v9
	v_pk_mul_f32 v[6:7], v[10:11], v[6:7]
	s_waitcnt vmcnt(6)
	v_lshlrev_b32_e32 v10, 16, v70
	v_pk_mul_f32 v[6:7], v[12:13], v[6:7]
	v_and_b32_e32 v13, 0xffff0000, v70
	v_cvt_pk_bf16_f32 v5, v6, v7
	v_lshlrev_b64 v[6:7], 12, v[108:109]
	v_lshl_add_u64 v[6:7], s[0:1], 0, v[6:7]
	v_lshl_add_u64 v[6:7], v[6:7], 0, v[110:111]
	global_store_dwordx4 v[6:7], v[2:5], off
	s_nop 1
	v_mul_lo_u32 v2, v112, s45
	v_lshlrev_b32_e32 v3, 4, v119
	v_add3_u32 v2, s4, v2, v3
	v_mul_f32_e32 v3, 0xbfb8aa3b, v10
	v_exp_f32_e32 v6, v3
	v_mul_f32_e32 v3, 0xbfb8aa3b, v13
	v_exp_f32_e32 v7, v3
	ds_read_b128 v[2:5], v2
	v_add_f32_e32 v6, 1.0, v6
	v_rcp_f32_e32 v14, v6
	v_add_f32_e32 v6, 1.0, v7
	v_rcp_f32_e32 v15, v6
	v_mul_lo_u32 v6, v106, s45
	v_add3_u32 v0, s4, v6, v0
	ds_read_b128 v[6:9], v0
	s_waitcnt lgkmcnt(1)
	v_and_b32_e32 v11, 0xffff0000, v2
	v_lshlrev_b32_e32 v12, 16, v2
	v_pk_mul_f32 v[10:11], v[12:13], v[10:11]
	v_lshlrev_b32_e32 v12, 16, v71
	v_pk_mul_f32 v[10:11], v[14:15], v[10:11]
	v_and_b32_e32 v15, 0xffff0000, v71
	v_mul_f32_e32 v0, 0xbfb8aa3b, v12
	v_exp_f32_e32 v0, v0
	v_mul_f32_e32 v2, 0xbfb8aa3b, v15
	v_exp_f32_e32 v13, v2
	v_cvt_pk_bf16_f32 v2, v10, v11
	v_add_f32_e32 v0, 1.0, v0
	v_rcp_f32_e32 v10, v0
	v_add_f32_e32 v0, 1.0, v13
	v_rcp_f32_e32 v11, v0
	v_and_b32_e32 v13, 0xffff0000, v3
	v_lshlrev_b32_e32 v14, 16, v3
	v_pk_mul_f32 v[12:13], v[14:15], v[12:13]
	v_and_b32_e32 v15, 0xffff0000, v72
	v_pk_mul_f32 v[10:11], v[10:11], v[12:13]
	v_lshlrev_b32_e32 v12, 16, v72
	v_mul_f32_e32 v0, 0xbfb8aa3b, v12
	v_exp_f32_e32 v0, v0
	v_mul_f32_e32 v3, 0xbfb8aa3b, v15
	v_exp_f32_e32 v13, v3
	v_cvt_pk_bf16_f32 v3, v10, v11
	v_add_f32_e32 v0, 1.0, v0
	v_rcp_f32_e32 v10, v0
	v_add_f32_e32 v0, 1.0, v13
	v_rcp_f32_e32 v11, v0
	v_and_b32_e32 v13, 0xffff0000, v4
	v_lshlrev_b32_e32 v14, 16, v4
	v_pk_mul_f32 v[12:13], v[14:15], v[12:13]
	v_and_b32_e32 v15, 0xffff0000, v73
	v_pk_mul_f32 v[10:11], v[10:11], v[12:13]
	v_lshlrev_b32_e32 v12, 16, v73
	v_mul_f32_e32 v0, 0xbfb8aa3b, v12
	v_exp_f32_e32 v0, v0
	v_mul_f32_e32 v4, 0xbfb8aa3b, v15
	v_exp_f32_e32 v13, v4
	v_cvt_pk_bf16_f32 v4, v10, v11
	v_add_f32_e32 v0, 1.0, v0
	v_rcp_f32_e32 v10, v0
	v_add_f32_e32 v0, 1.0, v13
	v_rcp_f32_e32 v11, v0
	v_and_b32_e32 v13, 0xffff0000, v5
	v_lshlrev_b32_e32 v14, 16, v5
	v_pk_mul_f32 v[12:13], v[14:15], v[12:13]
	s_waitcnt vmcnt(6)
	v_and_b32_e32 v15, 0xffff0000, v66
	v_pk_mul_f32 v[10:11], v[10:11], v[12:13]
	v_lshlrev_b32_e32 v12, 16, v66
	v_mul_f32_e32 v0, 0xbfb8aa3b, v12
	v_exp_f32_e32 v0, v0
	v_mul_f32_e32 v13, 0xbfb8aa3b, v15
	v_exp_f32_e32 v13, v13
	v_cvt_pk_bf16_f32 v5, v10, v11
	v_lshlrev_b64 v[10:11], 12, v[102:103]
	v_lshl_add_u64 v[10:11], s[0:1], 0, v[10:11]
	v_lshl_add_u64 v[10:11], v[10:11], 0, v[104:105]
	v_add_f32_e32 v0, 1.0, v0
	global_store_dwordx4 v[10:11], v[2:5], off
	s_waitcnt lgkmcnt(0)
	v_lshlrev_b32_e32 v14, 16, v6
	v_and_b32_e32 v11, 0xffff0000, v67
	v_rcp_f32_e32 v2, v0
	v_add_f32_e32 v0, 1.0, v13
	v_rcp_f32_e32 v3, v0
	v_and_b32_e32 v13, 0xffff0000, v6
	v_pk_mul_f32 v[4:5], v[14:15], v[12:13]
	v_lshlrev_b32_e32 v10, 16, v7
	v_pk_mul_f32 v[2:3], v[2:3], v[4:5]
	v_lshlrev_b32_e32 v4, 16, v67
	v_mul_f32_e32 v0, 0xbfb8aa3b, v4
	v_exp_f32_e32 v0, v0
	v_mul_f32_e32 v5, 0xbfb8aa3b, v11
	v_exp_f32_e32 v5, v5
	v_lshlrev_b32_e32 v6, 16, v68
	v_add_f32_e32 v0, 1.0, v0
	v_rcp_f32_e32 v12, v0
	v_add_f32_e32 v0, 1.0, v5
	v_and_b32_e32 v5, 0xffff0000, v7
	v_rcp_f32_e32 v13, v0
	v_pk_mul_f32 v[4:5], v[10:11], v[4:5]
	v_and_b32_e32 v11, 0xffff0000, v68
	v_mul_f32_e32 v0, 0xbfb8aa3b, v6
	v_cvt_pk_bf16_f32 v2, v2, v3
	v_exp_f32_e32 v0, v0
	v_mul_f32_e32 v3, 0xbfb8aa3b, v11
	v_exp_f32_e32 v7, v3
	v_pk_mul_f32 v[4:5], v[12:13], v[4:5]
	v_add_f32_e32 v0, 1.0, v0
	v_cvt_pk_bf16_f32 v3, v4, v5
	v_rcp_f32_e32 v4, v0
	v_add_f32_e32 v0, 1.0, v7
	v_rcp_f32_e32 v5, v0
	v_and_b32_e32 v7, 0xffff0000, v8
	v_lshlrev_b32_e32 v10, 16, v8
	v_pk_mul_f32 v[6:7], v[10:11], v[6:7]
	v_and_b32_e32 v11, 0xffff0000, v69
	v_pk_mul_f32 v[4:5], v[4:5], v[6:7]
	v_lshlrev_b32_e32 v6, 16, v69
	v_mul_f32_e32 v0, 0xbfb8aa3b, v6
	v_exp_f32_e32 v0, v0
	v_mul_f32_e32 v7, 0xbfb8aa3b, v11
	v_exp_f32_e32 v7, v7
	v_lshlrev_b32_e32 v10, 16, v9
	v_add_f32_e32 v0, 1.0, v0
	v_rcp_f32_e32 v12, v0
	v_add_f32_e32 v0, 1.0, v7
	v_rcp_f32_e32 v13, v0
	v_and_b32_e32 v7, 0xffff0000, v9
	v_pk_mul_f32 v[6:7], v[10:11], v[6:7]
	v_cvt_pk_bf16_f32 v4, v4, v5
	v_pk_mul_f32 v[6:7], v[12:13], v[6:7]
	s_nop 0
	v_cvt_pk_bf16_f32 v5, v6, v7
	v_lshlrev_b64 v[6:7], 12, v[98:99]
	v_lshl_add_u64 v[6:7], s[0:1], 0, v[6:7]
	v_lshl_add_u64 v[6:7], v[6:7], 0, v[100:101]
	global_store_dwordx4 v[6:7], v[2:5], off
	s_barrier
	s_nop 0
	v_ashrrev_i32_e32 v0, 31, v28
	v_lshrrev_b32_e32 v0, 28, v0
	v_add_u32_e32 v0, v28, v0
	v_ashrrev_i32_e32 v146, 4, v0
	v_and_b32_e32 v0, -16, v0
	v_sub_u32_e32 v29, v28, v0
	v_ashrrev_i32_e32 v147, 31, v146
	v_lshlrev_b32_e32 v4, 3, v29
	v_lshlrev_b64 v[2:3], 14, v[146:147]
	v_ashrrev_i32_e32 v5, 31, v4
	s_and_b32 s84, s49, 7
	s_lshl_b32 s84, s84, 22
	s_add_u32 s84, s84, 0x300000
	s_add_u32 s84, s20, s84
	s_addc_u32 s85, s21, 0
	s_mov_b32 s86, 0xfff02000
	v_lshl_add_u64 v[2:3], s[84:85], 0, v[2:3]
	v_lshlrev_b64 v[18:19], 1, v[4:5]
	v_lshl_add_u64 v[20:21], v[2:3], 0, v[18:19]
	v_add_co_u32_e32 v6, vcc, s43, v20
	v_add_u32_e32 v0, 0x200, v28
	s_nop 0
	v_addc_co_u32_e32 v7, vcc, 0, v21, vcc
	global_load_dwordx4 v[2:5], v[6:7], off offset:-4096
	s_nop 0
	global_load_dwordx4 v[6:9], v[6:7], off
	v_ashrrev_i32_e32 v10, 31, v0
	v_readfirstlane_b32 s4, v28
	v_lshrrev_b32_e32 v10, 28, v10
	s_ashr_i32 s22, s4, 1
	v_add_u32_e32 v10, v0, v10
	s_andn2_b32 s22, s22, 31
	v_ashrrev_i32_e32 v148, 4, v10
	v_and_b32_e32 v10, -16, v10
	s_ashr_i32 s34, s22, 31
	v_sub_u32_e32 v30, v0, v10
	s_add_u32 s4, s5, s22
	v_ashrrev_i32_e32 v149, 31, v148
	v_lshlrev_b32_e32 v12, 3, v30
	v_and_b32_e32 v31, 31, v28
	s_addc_u32 s5, s23, s34
	v_lshlrev_b64 v[10:11], 14, v[148:149]
	v_ashrrev_i32_e32 v13, 31, v12
	v_or_b32_e32 v26, s4, v31
	v_mov_b32_e32 v27, s5
	v_lshl_add_u64 v[10:11], s[84:85], 0, v[10:11]
	v_lshlrev_b64 v[22:23], 1, v[12:13]
	v_lshlrev_b64 v[26:27], 14, v[26:27]
	v_lshl_add_u64 v[24:25], v[10:11], 0, v[22:23]
	v_bfe_u32 v32, v28, 5, 1
	v_lshl_add_u64 v[26:27], s[12:13], 0, v[26:27]
	v_add_co_u32_e32 v14, vcc, s43, v24
	v_lshl_add_u64 v[26:27], v[26:27], 0, s[16:17]
	v_lshlrev_b32_e32 v0, 4, v32
	v_addc_co_u32_e32 v15, vcc, 0, v25, vcc
	v_lshl_add_u64 v[26:27], v[26:27], 0, v[0:1]
	v_mul_lo_u32 v149, v146, s45
	v_lshlrev_b32_e32 v156, 4, v29
	global_load_dwordx4 v[10:13], v[14:15], off offset:-4096
	s_nop 0
	global_load_dwordx4 v[14:17], v[14:15], off
	s_nop 0
	global_load_dwordx4 v[98:101], v[26:27], off
	global_load_dwordx4 v[102:105], v[26:27], off offset:32
	global_load_dwordx4 v[106:109], v[26:27], off offset:64
	global_load_dwordx4 v[110:113], v[26:27], off offset:96
	global_load_dwordx4 v[114:117], v[26:27], off offset:128
	global_load_dwordx4 v[118:121], v[26:27], off offset:160
	global_load_dwordx4 v[122:125], v[26:27], off offset:192
	global_load_dwordx4 v[126:129], v[26:27], off offset:224
	v_add3_u32 v26, 0, v149, v156
	s_waitcnt vmcnt(0)
	v_mul_lo_u32 v158, v148, s45
	v_lshlrev_b32_e32 v159, 4, v30
	v_lshlrev_b32_e32 v163, 2, v32
	v_add_u32_e32 v161, 0, v0
	s_add_i32 s7, s7, s22
	v_and_b32_e32 v147, 63, v28
	v_mad_u32_u24 v162, v31, s45, v161
	v_lshl_add_u32 v150, v146, 14, v18
	s_mov_b64 s[78:79], s[20:21]
	v_lshl_add_u32 v152, v148, 14, v22
	v_or_b32_e32 v195, s7, v31
	s_add_i32 s23, s33, 4
	v_mul_lo_u32 v157, v146, s46
	v_mul_lo_u32 v160, v148, s46
	s_add_i32 s27, s22, s27
	s_or_b32 s33, s33, 3
	v_or_b32_e32 v165, 32, v163
	v_or_b32_e32 v166, 33, v163
	v_or_b32_e32 v167, 2, v163
	v_or_b32_e32 v168, 34, v163
	v_or_b32_e32 v169, 3, v163
	v_or_b32_e32 v170, 35, v163
	v_or_b32_e32 v171, 8, v163
	v_or_b32_e32 v172, 40, v163
	v_or_b32_e32 v173, 9, v163
	v_or_b32_e32 v174, 41, v163
	v_or_b32_e32 v175, 10, v163
	v_or_b32_e32 v176, 42, v163
	v_or_b32_e32 v177, 11, v163
	v_or_b32_e32 v178, 43, v163
	v_or_b32_e32 v179, 16, v163
	v_or_b32_e32 v180, 48, v163
	v_or_b32_e32 v181, 17, v163
	v_or_b32_e32 v182, 49, v163
	v_or_b32_e32 v183, 18, v163
	v_or_b32_e32 v184, 50, v163
	v_or_b32_e32 v185, 19, v163
	v_or_b32_e32 v186, 51, v163
	v_or_b32_e32 v187, 24, v163
	v_or_b32_e32 v188, 56, v163
	ds_write_b128 v26, v[2:5]
	v_mad_u64_u32 v[2:3], s[34:35], v146, 48, v[26:27]
	ds_write_b128 v2, v[6:9] offset:34816
	v_add_co_u32_e32 v2, vcc, s86, v20
	v_mov_b32_e32 v4, v1
	s_nop 0
	v_addc_co_u32_e32 v3, vcc, -1, v21, vcc
	global_load_dwordx4 v[130:133], v[2:3], off offset:-4096
	global_load_dwordx4 v[134:137], v[2:3], off
	v_add_co_u32_e32 v2, vcc, s86, v24
	v_mov_b32_e32 v5, v1
	s_nop 0
	v_addc_co_u32_e32 v3, vcc, -1, v25, vcc
	global_load_dwordx4 v[138:141], v[2:3], off offset:-4096
	global_load_dwordx4 v[142:145], v[2:3], off
	v_add3_u32 v2, 0, v158, v159
	v_mov_b32_e32 v6, v1
	v_mov_b32_e32 v7, v1
	v_mov_b32_e32 v8, v1
	v_mov_b32_e32 v9, v1
	v_or_b32_e32 v189, 25, v163
	v_or_b32_e32 v190, 57, v163
	v_or_b32_e32 v191, 26, v163
	v_or_b32_e32 v192, 58, v163
	v_or_b32_e32 v193, 27, v163
	v_or_b32_e32 v194, 59, v163
	ds_write_b128 v2, v[10:13]
	v_mad_u64_u32 v[2:3], s[34:35], v148, 48, v[2:3]
	ds_write_b128 v2, v[14:17] offset:34816
	v_lshrrev_b32_e32 v2, 2, v28
	v_and_or_b32 v0, v2, 3, v163
	v_lshlrev_b32_e32 v2, 1, v28
	v_lshlrev_b32_e32 v3, 3, v28
	v_mad_u32_u24 v0, v0, s46, 0
	v_and_b32_e32 v2, 32, v2
	v_and_b32_e32 v3, 24, v3
	v_mov_b32_e32 v14, v1
	v_mov_b32_e32 v15, v1
	v_add3_u32 v164, v0, v2, v3
	v_mov_b32_e32 v0, v1
	v_mov_b32_e32 v2, v1
	v_mov_b32_e32 v3, v1
	v_mov_b32_e32 v10, v1
	v_mov_b32_e32 v11, v1
	v_mov_b32_e32 v12, v1
	v_mov_b32_e32 v13, v1
	v_mov_b64_e32 v[64:65], v[14:15]
	v_mov_b64_e32 v[48:49], v[14:15]
	v_mov_b64_e32 v[32:33], v[14:15]
	v_mov_b64_e32 v[62:63], v[12:13]
	v_mov_b64_e32 v[60:61], v[10:11]
	v_mov_b64_e32 v[58:59], v[8:9]
	v_mov_b64_e32 v[56:57], v[6:7]
	v_mov_b64_e32 v[54:55], v[4:5]
	v_mov_b64_e32 v[52:53], v[2:3]
	v_mov_b64_e32 v[50:51], v[0:1]
	v_mov_b64_e32 v[46:47], v[12:13]
	v_mov_b64_e32 v[44:45], v[10:11]
	v_mov_b64_e32 v[42:43], v[8:9]
	v_mov_b64_e32 v[40:41], v[6:7]
	v_mov_b64_e32 v[38:39], v[4:5]
	v_mov_b64_e32 v[36:37], v[2:3]
	v_mov_b64_e32 v[34:35], v[0:1]
	v_mov_b64_e32 v[30:31], v[12:13]
	v_mov_b64_e32 v[28:29], v[10:11]
	v_mov_b64_e32 v[26:27], v[8:9]
	v_mov_b64_e32 v[24:25], v[6:7]
	v_mov_b64_e32 v[22:23], v[4:5]
	v_mov_b64_e32 v[20:21], v[2:3]
	v_mov_b64_e32 v[18:19], v[0:1]
	v_mov_b64_e32 v[16:17], v[14:15]
	v_mov_b64_e32 v[14:15], v[12:13]
	v_mov_b64_e32 v[12:13], v[10:11]
	v_mov_b64_e32 v[10:11], v[8:9]
	v_mov_b64_e32 v[8:9], v[6:7]
	v_mov_b64_e32 v[6:7], v[4:5]
	v_mov_b64_e32 v[4:5], v[2:3]
	v_mov_b64_e32 v[2:3], v[0:1]
	s_waitcnt lgkmcnt(0)
	s_movk_i32 s68, 0x5000
	s_mov_b32 s69, 0
	s_mov_b32 s70, 0xe800
	s_mov_b32 s72, 0
	s_lshl_b32 s77, s33, 6
	v_subrev_u32_e32 v195, s77, v195
	s_barrier
	v_readfirstlane_b32 s73, v255
	s_cmp_lt_u32 s73, 0x100
	s_cbranch_scc1 .Lyp657
	s_setprio 1

.LBB0_657:
	s_add_i32 s7, s25, -2
	s_and_b32 s7, s7, 1
	s_xor_b32 s20, s7, 1
	s_mul_i32 s21, s20, 0x4400
	s_add_i32 s21, s21, 0
	s_mulk_i32 s20, 0xc00
	s_add_i32 s20, s21, s20
	v_add3_u32 v0, s21, v149, v156
	s_waitcnt vmcnt(3)
	ds_write_b128 v0, v[130:133]
	v_add3_u32 v0, s68, v157, v156
	s_waitcnt vmcnt(2)
	ds_write_b128 v0, v[134:137] offset:34816
	v_add3_u32 v0, s21, v158, v159
	s_cmp_lt_u32 s25, s23
	s_waitcnt vmcnt(1)
	ds_write_b128 v0, v[138:141]
	v_add3_u32 v0, s68, v160, v159
	s_cselect_b32 s20, s25, s33
	s_sub_i32 s20, s33, s20
	s_lshl_b32 s20, s20, 20
	s_add_u32 s80, s78, s20
	s_addc_u32 s81, s79, 0
	s_add_u32 s80, s80, 0x1000
	s_addc_u32 s81, s81, 0
	s_add_u32 s82, s80, 0x1000
	s_addc_u32 s83, s81, 0
	s_waitcnt vmcnt(0)
	ds_write_b128 v0, v[142:145] offset:34816
	global_load_dwordx4 v[130:133], v150, s[80:81]
	global_load_dwordx4 v[134:137], v150, s[82:83]
	s_sub_i32 s20, s26, 63
	s_cmp_gt_i32 s20, s27
	global_load_dwordx4 v[138:141], v152, s[80:81]
	global_load_dwordx4 v[142:145], v152, s[82:83]
	s_lshr_b32 s77, s6, 2
	s_sub_i32 s77, s77, s26
	s_add_i32 s77, s77, -1
	s_sub_i32 s75, s6, s24
	s_add_i32 s75, s75, -256
	s_cmp_gt_i32 s77, s27
	s_cbranch_scc1 .Lff2a_inact
	s_cmp_eq_u32 s72, 0
	s_cbranch_scc1 .Lff2a_first
	s_mul_i32 s20, s7, 0x4400
	v_add_u32_e32 v0, s20, v162
	ds_read_b128 v[198:201], v0
	ds_read_b128 v[202:205], v0 offset:32
	ds_read_b128 v[206:209], v0 offset:8704
	ds_read_b128 v[210:213], v0 offset:8736
	v_add_u32_e32 v246, s75, v161
	v_add_u32_e32 v234, 0x12800, v246
	v_add_u32_e32 v235, 0x12880, v246
	v_add_u32_e32 v238, 0x12820, v246
	v_add_u32_e32 v239, 0x128a0, v246
	v_add_u32_e32 v242, 0x12840, v246
	v_add_u32_e32 v243, 0x128c0, v246
	v_add_u32_e32 v247, 0x12860, v246
	v_add_u32_e32 v246, 0x128e0, v246
	ds_read_b128 v[218:221], v234
	ds_read_b128 v[234:237], v235
	ds_read_b128 v[222:225], v238
	ds_read_b128 v[238:241], v239
	ds_read_b128 v[226:229], v242
	ds_read_b128 v[242:245], v243
	ds_read_b128 v[230:233], v247
	ds_read_b128 v[246:249], v246
	s_waitcnt lgkmcnt(1)
	v_mfma_f32_32x32x16_bf16 v[218:233], v[198:201], v[98:101], v[218:233]
	v_sub_f32_e32 v82, v82, v197
	v_sub_f32_e32 v83, v83, v197
	v_sub_f32_e32 v84, v84, v197
	v_sub_f32_e32 v85, v85, v197
	v_exp_f32_e32 v82, v82
	v_exp_f32_e32 v83, v83
	v_exp_f32_e32 v84, v84
	v_exp_f32_e32 v85, v85
	s_waitcnt lgkmcnt(0)
	v_mfma_f32_32x32x16_bf16 v[234:249], v[206:209], v[98:101], v[234:249]
	v_sub_f32_e32 v86, v86, v197
	v_sub_f32_e32 v87, v87, v197
	v_sub_f32_e32 v88, v88, v197
	v_sub_f32_e32 v89, v89, v197
	v_exp_f32_e32 v86, v86
	v_exp_f32_e32 v87, v87
	v_exp_f32_e32 v88, v88
	v_exp_f32_e32 v89, v89
	v_mfma_f32_32x32x16_bf16 v[218:233], v[202:205], v[102:105], v[218:233]
	v_sub_f32_e32 v66, v66, v197
	v_sub_f32_e32 v67, v67, v197
	v_sub_f32_e32 v68, v68, v197
	v_sub_f32_e32 v69, v69, v197
	v_exp_f32_e32 v66, v66
	v_exp_f32_e32 v67, v67
	v_exp_f32_e32 v68, v68
	v_exp_f32_e32 v69, v69
	ds_read_b128 v[198:201], v0 offset:64
	ds_read_b128 v[202:205], v0 offset:96
	ds_read_b128 v[206:209], v0 offset:8768
	ds_read_b128 v[214:217], v0 offset:8800
	v_mfma_f32_32x32x16_bf16 v[234:249], v[210:213], v[102:105], v[234:249]
	v_add_f32_e32 v250, v82, v86
	v_add_f32_e32 v251, v83, v87
	v_add_f32_e32 v252, v84, v88
	v_add_f32_e32 v253, v85, v89
	v_sub_f32_e32 v70, v70, v197
	v_sub_f32_e32 v71, v71, v197
	v_sub_f32_e32 v72, v72, v197
	v_sub_f32_e32 v73, v73, v197
	s_waitcnt lgkmcnt(3)
	v_mfma_f32_32x32x16_bf16 v[218:233], v[198:201], v[106:109], v[218:233]
	v_exp_f32_e32 v70, v70
	v_exp_f32_e32 v71, v71
	v_exp_f32_e32 v72, v72
	v_exp_f32_e32 v73, v73
	v_add_f32_e32 v250, v250, v66
	v_add_f32_e32 v251, v251, v67
	v_add_f32_e32 v252, v252, v68
	v_add_f32_e32 v253, v253, v69
	s_waitcnt lgkmcnt(1)
	v_mfma_f32_32x32x16_bf16 v[234:249], v[206:209], v[106:109], v[234:249]
	v_sub_f32_e32 v90, v90, v197
	v_sub_f32_e32 v91, v91, v197
	v_sub_f32_e32 v92, v92, v197
	v_sub_f32_e32 v93, v93, v197
	v_exp_f32_e32 v90, v90
	v_exp_f32_e32 v91, v91
	v_exp_f32_e32 v92, v92
	v_exp_f32_e32 v93, v93
	v_mfma_f32_32x32x16_bf16 v[218:233], v[202:205], v[110:113], v[218:233]
	v_add_f32_e32 v250, v250, v70
	v_add_f32_e32 v251, v251, v71
	v_add_f32_e32 v252, v252, v72
	v_add_f32_e32 v253, v253, v73
	v_sub_f32_e32 v94, v94, v197
	v_sub_f32_e32 v95, v95, v197
	v_sub_f32_e32 v96, v96, v197
	v_sub_f32_e32 v97, v97, v197
	ds_read_b128 v[198:201], v0 offset:128
	ds_read_b128 v[202:205], v0 offset:160
	ds_read_b128 v[206:209], v0 offset:8832
	ds_read_b128 v[210:213], v0 offset:8864
	s_waitcnt lgkmcnt(4)
	v_mfma_f32_32x32x16_bf16 v[234:249], v[214:217], v[110:113], v[234:249]
	v_exp_f32_e32 v94, v94
	v_exp_f32_e32 v95, v95
	v_exp_f32_e32 v96, v96
	v_exp_f32_e32 v97, v97
	v_add_f32_e32 v250, v250, v90
	v_add_f32_e32 v251, v251, v91
	v_add_f32_e32 v252, v252, v92
	v_add_f32_e32 v253, v253, v93
	s_waitcnt lgkmcnt(3)
	v_mfma_f32_32x32x16_bf16 v[218:233], v[198:201], v[114:117], v[218:233]
	v_sub_f32_e32 v74, v74, v197
	v_sub_f32_e32 v75, v75, v197
	v_sub_f32_e32 v76, v76, v197
	v_sub_f32_e32 v77, v77, v197
	v_exp_f32_e32 v74, v74
	v_exp_f32_e32 v75, v75
	v_exp_f32_e32 v76, v76
	v_exp_f32_e32 v77, v77
	s_waitcnt lgkmcnt(1)
	v_mfma_f32_32x32x16_bf16 v[234:249], v[206:209], v[114:117], v[234:249]
	v_add_f32_e32 v250, v250, v94
	v_add_f32_e32 v251, v251, v95
	v_add_f32_e32 v252, v252, v96
	v_add_f32_e32 v253, v253, v97
	v_sub_f32_e32 v78, v78, v197
	v_sub_f32_e32 v79, v79, v197
	v_sub_f32_e32 v80, v80, v197
	v_sub_f32_e32 v81, v81, v197
	v_mfma_f32_32x32x16_bf16 v[218:233], v[202:205], v[118:121], v[218:233]
	v_exp_f32_e32 v78, v78
	v_exp_f32_e32 v79, v79
	v_exp_f32_e32 v80, v80
	v_exp_f32_e32 v81, v81
	v_add_f32_e32 v250, v250, v74
	v_add_f32_e32 v251, v251, v75
	v_add_f32_e32 v252, v252, v76
	v_add_f32_e32 v253, v253, v77
	ds_read_b128 v[198:201], v0 offset:192
	ds_read_b128 v[202:205], v0 offset:224
	ds_read_b128 v[206:209], v0 offset:8896
	ds_read_b128 v[214:217], v0 offset:8928
	s_waitcnt lgkmcnt(4)
	v_mfma_f32_32x32x16_bf16 v[234:249], v[210:213], v[118:121], v[234:249]
	v_add_f32_e32 v250, v250, v78
	v_add_f32_e32 v251, v251, v79
	v_add_f32_e32 v252, v252, v80
	v_add_f32_e32 v253, v253, v81
	v_add_f32_e32 v250, v250, v251
	v_add_f32_e32 v252, v252, v253
	v_add_f32_e32 v250, v250, v252
	v_add_f32_e32 v196, v196, v250
	s_waitcnt lgkmcnt(3)
	v_mfma_f32_32x32x16_bf16 v[218:233], v[198:201], v[122:125], v[218:233]
	v_cvt_pk_bf16_f32 v73, v72, v73
	v_cvt_pk_bf16_f32 v72, v70, v71
	v_cvt_pk_bf16_f32 v71, v68, v69
	v_cvt_pk_bf16_f32 v70, v66, v67
	v_cvt_pk_bf16_f32 v66, v82, v83
	v_cvt_pk_bf16_f32 v67, v84, v85
	v_cvt_pk_bf16_f32 v68, v86, v87
	v_cvt_pk_bf16_f32 v69, v88, v89
	s_waitcnt lgkmcnt(1)
	v_mfma_f32_32x32x16_bf16 v[234:249], v[206:209], v[122:125], v[234:249]
	v_cvt_pk_bf16_f32 v81, v80, v81
	v_cvt_pk_bf16_f32 v80, v78, v79
	v_cvt_pk_bf16_f32 v79, v76, v77
	v_cvt_pk_bf16_f32 v78, v74, v75
	v_cvt_pk_bf16_f32 v74, v90, v91
	v_cvt_pk_bf16_f32 v75, v92, v93
	v_cvt_pk_bf16_f32 v76, v94, v95
	v_cvt_pk_bf16_f32 v77, v96, v97
	v_mfma_f32_32x32x16_bf16 v[218:233], v[202:205], v[126:129], v[218:233]
	s_waitcnt lgkmcnt(0)
	v_mfma_f32_32x32x16_bf16 v[234:249], v[214:217], v[126:129], v[234:249]
	s_add_i32 s76, s77, 63
	s_cmp_le_i32 s76, s27
	s_cbranch_scc1 .Lff2a_z2
	v_cmp_le_i32_e32 vcc, v165, v195
	s_nop 8
	v_cndmask_b32_e32 v234, v155, v234, vcc
	v_cmp_lt_i32_e32 vcc, v163, v195
	s_nop 1
	v_cndmask_b32_e32 v219, v155, v219, vcc
	v_cmp_le_i32_e32 vcc, v163, v195
	s_nop 1
	v_cndmask_b32_e32 v218, v155, v218, vcc
	v_cmp_le_i32_e32 vcc, v166, v195
	s_nop 1
	v_cndmask_b32_e32 v235, v155, v235, vcc
	v_cmp_le_i32_e32 vcc, v167, v195
	s_nop 1
	v_cndmask_b32_e32 v220, v155, v220, vcc
	v_cmp_le_i32_e32 vcc, v168, v195
	s_nop 1
	v_cndmask_b32_e32 v236, v155, v236, vcc
	v_cmp_le_i32_e32 vcc, v169, v195
	s_nop 1
	v_cndmask_b32_e32 v221, v155, v221, vcc
	v_cmp_le_i32_e32 vcc, v170, v195
	s_nop 1
	v_cndmask_b32_e32 v237, v155, v237, vcc
	v_cmp_le_i32_e32 vcc, v171, v195
	s_nop 1
	v_cndmask_b32_e32 v222, v155, v222, vcc
	v_cmp_le_i32_e32 vcc, v172, v195
	s_nop 1
	v_cndmask_b32_e32 v238, v155, v238, vcc
	v_cmp_le_i32_e32 vcc, v173, v195
	s_nop 1
	v_cndmask_b32_e32 v223, v155, v223, vcc
	v_cmp_le_i32_e32 vcc, v174, v195
	s_nop 1
	v_cndmask_b32_e32 v239, v155, v239, vcc
	v_cmp_le_i32_e32 vcc, v175, v195
	s_nop 1
	v_cndmask_b32_e32 v224, v155, v224, vcc
	v_cmp_le_i32_e32 vcc, v176, v195
	s_nop 1
	v_cndmask_b32_e32 v240, v155, v240, vcc
	v_cmp_le_i32_e32 vcc, v177, v195
	s_nop 1
	v_cndmask_b32_e32 v225, v155, v225, vcc
	v_cmp_le_i32_e32 vcc, v178, v195
	s_nop 1
	v_cndmask_b32_e32 v241, v155, v241, vcc
	v_cmp_le_i32_e32 vcc, v179, v195
	s_nop 1
	v_cndmask_b32_e32 v226, v155, v226, vcc
	v_cmp_le_i32_e32 vcc, v180, v195
	s_nop 1
	v_cndmask_b32_e32 v242, v155, v242, vcc
	v_cmp_le_i32_e32 vcc, v181, v195
	s_nop 1
	v_cndmask_b32_e32 v227, v155, v227, vcc
	v_cmp_le_i32_e32 vcc, v182, v195
	s_nop 1
	v_cndmask_b32_e32 v243, v155, v243, vcc
	v_cmp_le_i32_e32 vcc, v183, v195
	s_nop 1
	v_cndmask_b32_e32 v228, v155, v228, vcc
	v_cmp_le_i32_e32 vcc, v184, v195
	s_nop 1
	v_cndmask_b32_e32 v244, v155, v244, vcc
	v_cmp_le_i32_e32 vcc, v185, v195
	s_nop 1
	v_cndmask_b32_e32 v229, v155, v229, vcc
	v_cmp_le_i32_e32 vcc, v186, v195
	s_nop 1
	v_cndmask_b32_e32 v245, v155, v245, vcc
	v_cmp_le_i32_e32 vcc, v187, v195
	s_nop 1
	v_cndmask_b32_e32 v230, v155, v230, vcc
	v_cmp_le_i32_e32 vcc, v188, v195
	s_nop 1
	v_cndmask_b32_e32 v246, v155, v246, vcc
	v_cmp_le_i32_e32 vcc, v189, v195
	s_nop 1
	v_cndmask_b32_e32 v231, v155, v231, vcc
	v_cmp_le_i32_e32 vcc, v190, v195
	s_nop 1
	v_cndmask_b32_e32 v247, v155, v247, vcc
	v_cmp_le_i32_e32 vcc, v191, v195
	s_nop 1
	v_cndmask_b32_e32 v232, v155, v232, vcc
	v_cmp_le_i32_e32 vcc, v192, v195
	s_nop 1
	v_cndmask_b32_e32 v248, v155, v248, vcc
	v_cmp_le_i32_e32 vcc, v193, v195
	s_nop 1
	v_cndmask_b32_e32 v233, v155, v233, vcc
	v_cmp_le_i32_e32 vcc, v194, v195
	s_nop 1
	v_cndmask_b32_e32 v249, v155, v249, vcc

.Lff2a_first:
	s_mul_i32 s20, s7, 0x4400
	v_add_u32_e32 v0, s20, v162
	ds_read_b128 v[198:201], v0
	ds_read_b128 v[202:205], v0 offset:32
	ds_read_b128 v[206:209], v0 offset:8704
	ds_read_b128 v[210:213], v0 offset:8736
	v_add_u32_e32 v246, s75, v161
	v_add_u32_e32 v234, 0x12800, v246
	v_add_u32_e32 v235, 0x12880, v246
	v_add_u32_e32 v238, 0x12820, v246
	v_add_u32_e32 v239, 0x128a0, v246
	v_add_u32_e32 v242, 0x12840, v246
	v_add_u32_e32 v243, 0x128c0, v246
	v_add_u32_e32 v247, 0x12860, v246
	v_add_u32_e32 v246, 0x128e0, v246
	ds_read_b128 v[218:221], v234
	ds_read_b128 v[234:237], v235
	ds_read_b128 v[222:225], v238
	ds_read_b128 v[238:241], v239
	ds_read_b128 v[226:229], v242
	ds_read_b128 v[242:245], v243
	ds_read_b128 v[230:233], v247
	ds_read_b128 v[246:249], v246
	s_waitcnt lgkmcnt(1)
	v_mfma_f32_32x32x16_bf16 v[218:233], v[198:201], v[98:101], v[218:233]
	s_waitcnt lgkmcnt(0)
	v_mfma_f32_32x32x16_bf16 v[234:249], v[206:209], v[98:101], v[234:249]
	v_mfma_f32_32x32x16_bf16 v[218:233], v[202:205], v[102:105], v[218:233]
	ds_read_b128 v[198:201], v0 offset:64
	ds_read_b128 v[202:205], v0 offset:96
	ds_read_b128 v[206:209], v0 offset:8768
	ds_read_b128 v[214:217], v0 offset:8800
	v_mfma_f32_32x32x16_bf16 v[234:249], v[210:213], v[102:105], v[234:249]
	s_waitcnt lgkmcnt(3)
	v_mfma_f32_32x32x16_bf16 v[218:233], v[198:201], v[106:109], v[218:233]
	s_waitcnt lgkmcnt(1)
	v_mfma_f32_32x32x16_bf16 v[234:249], v[206:209], v[106:109], v[234:249]
	v_mfma_f32_32x32x16_bf16 v[218:233], v[202:205], v[110:113], v[218:233]
	ds_read_b128 v[198:201], v0 offset:128
	ds_read_b128 v[202:205], v0 offset:160
	ds_read_b128 v[206:209], v0 offset:8832
	ds_read_b128 v[210:213], v0 offset:8864
	s_waitcnt lgkmcnt(4)
	v_mfma_f32_32x32x16_bf16 v[234:249], v[214:217], v[110:113], v[234:249]
	s_waitcnt lgkmcnt(3)
	v_mfma_f32_32x32x16_bf16 v[218:233], v[198:201], v[114:117], v[218:233]
	s_waitcnt lgkmcnt(1)
	v_mfma_f32_32x32x16_bf16 v[234:249], v[206:209], v[114:117], v[234:249]
	v_mfma_f32_32x32x16_bf16 v[218:233], v[202:205], v[118:121], v[218:233]
	ds_read_b128 v[198:201], v0 offset:192
	ds_read_b128 v[202:205], v0 offset:224
	ds_read_b128 v[206:209], v0 offset:8896
	ds_read_b128 v[214:217], v0 offset:8928
	s_waitcnt lgkmcnt(4)
	v_mfma_f32_32x32x16_bf16 v[234:249], v[210:213], v[118:121], v[234:249]
	s_waitcnt lgkmcnt(3)
	v_mfma_f32_32x32x16_bf16 v[218:233], v[198:201], v[122:125], v[218:233]
	s_waitcnt lgkmcnt(1)
	v_mfma_f32_32x32x16_bf16 v[234:249], v[206:209], v[122:125], v[234:249]
	v_mfma_f32_32x32x16_bf16 v[218:233], v[202:205], v[126:129], v[218:233]
	s_waitcnt lgkmcnt(0)
	v_mfma_f32_32x32x16_bf16 v[234:249], v[214:217], v[126:129], v[234:249]
	s_add_i32 s76, s77, 63
	s_cmp_le_i32 s76, s27
	s_cbranch_scc1 .Lff2a_m1
	v_cmp_le_i32_e32 vcc, v165, v195
	s_nop 8
	v_cndmask_b32_e32 v234, v155, v234, vcc
	v_cmp_lt_i32_e32 vcc, v163, v195
	s_nop 1
	v_cndmask_b32_e32 v219, v155, v219, vcc
	v_cmp_le_i32_e32 vcc, v163, v195
	s_nop 1
	v_cndmask_b32_e32 v218, v155, v218, vcc
	v_cmp_le_i32_e32 vcc, v166, v195
	s_nop 1
	v_cndmask_b32_e32 v235, v155, v235, vcc
	v_cmp_le_i32_e32 vcc, v167, v195
	s_nop 1
	v_cndmask_b32_e32 v220, v155, v220, vcc
	v_cmp_le_i32_e32 vcc, v168, v195
	s_nop 1
	v_cndmask_b32_e32 v236, v155, v236, vcc
	v_cmp_le_i32_e32 vcc, v169, v195
	s_nop 1
	v_cndmask_b32_e32 v221, v155, v221, vcc
	v_cmp_le_i32_e32 vcc, v170, v195
	s_nop 1
	v_cndmask_b32_e32 v237, v155, v237, vcc
	v_cmp_le_i32_e32 vcc, v171, v195
	s_nop 1
	v_cndmask_b32_e32 v222, v155, v222, vcc
	v_cmp_le_i32_e32 vcc, v172, v195
	s_nop 1
	v_cndmask_b32_e32 v238, v155, v238, vcc
	v_cmp_le_i32_e32 vcc, v173, v195
	s_nop 1
	v_cndmask_b32_e32 v223, v155, v223, vcc
	v_cmp_le_i32_e32 vcc, v174, v195
	s_nop 1
	v_cndmask_b32_e32 v239, v155, v239, vcc
	v_cmp_le_i32_e32 vcc, v175, v195
	s_nop 1
	v_cndmask_b32_e32 v224, v155, v224, vcc
	v_cmp_le_i32_e32 vcc, v176, v195
	s_nop 1
	v_cndmask_b32_e32 v240, v155, v240, vcc
	v_cmp_le_i32_e32 vcc, v177, v195
	s_nop 1
	v_cndmask_b32_e32 v225, v155, v225, vcc
	v_cmp_le_i32_e32 vcc, v178, v195
	s_nop 1
	v_cndmask_b32_e32 v241, v155, v241, vcc
	v_cmp_le_i32_e32 vcc, v179, v195
	s_nop 1
	v_cndmask_b32_e32 v226, v155, v226, vcc
	v_cmp_le_i32_e32 vcc, v180, v195
	s_nop 1
	v_cndmask_b32_e32 v242, v155, v242, vcc
	v_cmp_le_i32_e32 vcc, v181, v195
	s_nop 1
	v_cndmask_b32_e32 v227, v155, v227, vcc
	v_cmp_le_i32_e32 vcc, v182, v195
	s_nop 1
	v_cndmask_b32_e32 v243, v155, v243, vcc
	v_cmp_le_i32_e32 vcc, v183, v195
	s_nop 1
	v_cndmask_b32_e32 v228, v155, v228, vcc
	v_cmp_le_i32_e32 vcc, v184, v195
	s_nop 1
	v_cndmask_b32_e32 v244, v155, v244, vcc
	v_cmp_le_i32_e32 vcc, v185, v195
	s_nop 1
	v_cndmask_b32_e32 v229, v155, v229, vcc
	v_cmp_le_i32_e32 vcc, v186, v195
	s_nop 1
	v_cndmask_b32_e32 v245, v155, v245, vcc
	v_cmp_le_i32_e32 vcc, v187, v195
	s_nop 1
	v_cndmask_b32_e32 v230, v155, v230, vcc
	v_cmp_le_i32_e32 vcc, v188, v195
	s_nop 1
	v_cndmask_b32_e32 v246, v155, v246, vcc
	v_cmp_le_i32_e32 vcc, v189, v195
	s_nop 1
	v_cndmask_b32_e32 v231, v155, v231, vcc
	v_cmp_le_i32_e32 vcc, v190, v195
	s_nop 1
	v_cndmask_b32_e32 v247, v155, v247, vcc
	v_cmp_le_i32_e32 vcc, v191, v195
	s_nop 1
	v_cndmask_b32_e32 v232, v155, v232, vcc
	v_cmp_le_i32_e32 vcc, v192, v195
	s_nop 1
	v_cndmask_b32_e32 v248, v155, v248, vcc
	v_cmp_le_i32_e32 vcc, v193, v195
	s_nop 1
	v_cndmask_b32_e32 v233, v155, v233, vcc
	v_cmp_le_i32_e32 vcc, v194, v195
	s_nop 1
	v_cndmask_b32_e32 v249, v155, v249, vcc

.Lff2a_bar:
	s_waitcnt lgkmcnt(0)
	s_barrier
	s_mov_b32 s71, s70
	s_mov_b32 s70, s69
	s_mov_b32 s69, s68
	s_mov_b32 s68, s71
	s_addk_i32 s24, 0x100
	s_add_i32 s26, s26, 64
	s_add_i32 s25, s25, 1
	s_cmp_lg_u32 s6, s24
	v_add_u32_e32 v195, 64, v195
	s_cbranch_scc0 .Lff2a_exit
	s_branch .Lff2b_top

.Lff2b_top:
	s_add_i32 s7, s25, -2
	s_and_b32 s7, s7, 1
	s_xor_b32 s20, s7, 1
	s_mul_i32 s21, s20, 0x4400
	s_add_i32 s21, s21, 0
	s_mulk_i32 s20, 0xc00
	s_add_i32 s20, s21, s20
	v_add3_u32 v0, s21, v149, v156
	s_waitcnt vmcnt(3)
	ds_write_b128 v0, v[130:133]
	v_add3_u32 v0, s68, v157, v156
	s_waitcnt vmcnt(2)
	ds_write_b128 v0, v[134:137] offset:34816
	v_add3_u32 v0, s21, v158, v159
	s_cmp_lt_u32 s25, s23
	s_waitcnt vmcnt(1)
	ds_write_b128 v0, v[138:141]
	v_add3_u32 v0, s68, v160, v159
	s_cselect_b32 s20, s25, s33
	s_sub_i32 s20, s33, s20
	s_lshl_b32 s20, s20, 20
	s_add_u32 s80, s78, s20
	s_addc_u32 s81, s79, 0
	s_add_u32 s80, s80, 0x1000
	s_addc_u32 s81, s81, 0
	s_add_u32 s82, s80, 0x1000
	s_addc_u32 s83, s81, 0
	s_waitcnt vmcnt(0)
	ds_write_b128 v0, v[142:145] offset:34816
	global_load_dwordx4 v[130:133], v150, s[80:81]
	global_load_dwordx4 v[134:137], v150, s[82:83]
	s_sub_i32 s20, s26, 63
	s_cmp_gt_i32 s20, s27
	global_load_dwordx4 v[138:141], v152, s[80:81]
	global_load_dwordx4 v[142:145], v152, s[82:83]
	s_lshr_b32 s77, s6, 2
	s_sub_i32 s77, s77, s26
	s_add_i32 s77, s77, -1
	s_sub_i32 s75, s6, s24
	s_add_i32 s75, s75, -256
	s_cmp_gt_i32 s77, s27
	s_cbranch_scc1 .Lff2b_inact
	s_cmp_eq_u32 s72, 0
	s_cbranch_scc1 .Lff2b_first
	s_mul_i32 s20, s7, 0x4400
	v_add_u32_e32 v0, s20, v162
	ds_read_b128 v[198:201], v0
	ds_read_b128 v[202:205], v0 offset:32
	ds_read_b128 v[206:209], v0 offset:8704
	ds_read_b128 v[210:213], v0 offset:8736
	v_add_u32_e32 v78, s75, v161
	v_add_u32_e32 v66, 0x12800, v78
	v_add_u32_e32 v67, 0x12880, v78
	v_add_u32_e32 v70, 0x12820, v78
	v_add_u32_e32 v71, 0x128a0, v78
	v_add_u32_e32 v74, 0x12840, v78
	v_add_u32_e32 v75, 0x128c0, v78
	v_add_u32_e32 v79, 0x12860, v78
	v_add_u32_e32 v78, 0x128e0, v78
	ds_read_b128 v[82:85], v66
	ds_read_b128 v[66:69], v67
	ds_read_b128 v[86:89], v70
	ds_read_b128 v[70:73], v71
	ds_read_b128 v[90:93], v74
	ds_read_b128 v[74:77], v75
	ds_read_b128 v[94:97], v79
	ds_read_b128 v[78:81], v78
	s_waitcnt lgkmcnt(1)
	v_mfma_f32_32x32x16_bf16 v[82:97], v[198:201], v[98:101], v[82:97]
	v_sub_f32_e32 v218, v218, v197
	v_sub_f32_e32 v219, v219, v197
	v_sub_f32_e32 v220, v220, v197
	v_sub_f32_e32 v221, v221, v197
	v_exp_f32_e32 v218, v218
	v_exp_f32_e32 v219, v219
	v_exp_f32_e32 v220, v220
	v_exp_f32_e32 v221, v221
	s_waitcnt lgkmcnt(0)
	v_mfma_f32_32x32x16_bf16 v[66:81], v[206:209], v[98:101], v[66:81]
	v_sub_f32_e32 v222, v222, v197
	v_sub_f32_e32 v223, v223, v197
	v_sub_f32_e32 v224, v224, v197
	v_sub_f32_e32 v225, v225, v197
	v_exp_f32_e32 v222, v222
	v_exp_f32_e32 v223, v223
	v_exp_f32_e32 v224, v224
	v_exp_f32_e32 v225, v225
	v_mfma_f32_32x32x16_bf16 v[82:97], v[202:205], v[102:105], v[82:97]
	v_sub_f32_e32 v234, v234, v197
	v_sub_f32_e32 v235, v235, v197
	v_sub_f32_e32 v236, v236, v197
	v_sub_f32_e32 v237, v237, v197
	v_exp_f32_e32 v234, v234
	v_exp_f32_e32 v235, v235
	v_exp_f32_e32 v236, v236
	v_exp_f32_e32 v237, v237
	ds_read_b128 v[198:201], v0 offset:64
	ds_read_b128 v[202:205], v0 offset:96
	ds_read_b128 v[206:209], v0 offset:8768
	ds_read_b128 v[214:217], v0 offset:8800
	v_mfma_f32_32x32x16_bf16 v[66:81], v[210:213], v[102:105], v[66:81]
	v_add_f32_e32 v250, v218, v222
	v_add_f32_e32 v251, v219, v223
	v_add_f32_e32 v252, v220, v224
	v_add_f32_e32 v253, v221, v225
	v_sub_f32_e32 v238, v238, v197
	v_sub_f32_e32 v239, v239, v197
	v_sub_f32_e32 v240, v240, v197
	v_sub_f32_e32 v241, v241, v197
	s_waitcnt lgkmcnt(3)
	v_mfma_f32_32x32x16_bf16 v[82:97], v[198:201], v[106:109], v[82:97]
	v_exp_f32_e32 v238, v238
	v_exp_f32_e32 v239, v239
	v_exp_f32_e32 v240, v240
	v_exp_f32_e32 v241, v241
	v_add_f32_e32 v250, v250, v234
	v_add_f32_e32 v251, v251, v235
	v_add_f32_e32 v252, v252, v236
	v_add_f32_e32 v253, v253, v237
	s_waitcnt lgkmcnt(1)
	v_mfma_f32_32x32x16_bf16 v[66:81], v[206:209], v[106:109], v[66:81]
	v_sub_f32_e32 v226, v226, v197
	v_sub_f32_e32 v227, v227, v197
	v_sub_f32_e32 v228, v228, v197
	v_sub_f32_e32 v229, v229, v197
	v_exp_f32_e32 v226, v226
	v_exp_f32_e32 v227, v227
	v_exp_f32_e32 v228, v228
	v_exp_f32_e32 v229, v229
	v_mfma_f32_32x32x16_bf16 v[82:97], v[202:205], v[110:113], v[82:97]
	v_add_f32_e32 v250, v250, v238
	v_add_f32_e32 v251, v251, v239
	v_add_f32_e32 v252, v252, v240
	v_add_f32_e32 v253, v253, v241
	v_sub_f32_e32 v230, v230, v197
	v_sub_f32_e32 v231, v231, v197
	v_sub_f32_e32 v232, v232, v197
	v_sub_f32_e32 v233, v233, v197
	ds_read_b128 v[198:201], v0 offset:128
	ds_read_b128 v[202:205], v0 offset:160
	ds_read_b128 v[206:209], v0 offset:8832
	ds_read_b128 v[210:213], v0 offset:8864
	s_waitcnt lgkmcnt(4)
	v_mfma_f32_32x32x16_bf16 v[66:81], v[214:217], v[110:113], v[66:81]
	v_exp_f32_e32 v230, v230
	v_exp_f32_e32 v231, v231
	v_exp_f32_e32 v232, v232
	v_exp_f32_e32 v233, v233
	v_add_f32_e32 v250, v250, v226
	v_add_f32_e32 v251, v251, v227
	v_add_f32_e32 v252, v252, v228
	v_add_f32_e32 v253, v253, v229
	s_waitcnt lgkmcnt(3)
	v_mfma_f32_32x32x16_bf16 v[82:97], v[198:201], v[114:117], v[82:97]
	v_sub_f32_e32 v242, v242, v197
	v_sub_f32_e32 v243, v243, v197
	v_sub_f32_e32 v244, v244, v197
	v_sub_f32_e32 v245, v245, v197
	v_exp_f32_e32 v242, v242
	v_exp_f32_e32 v243, v243
	v_exp_f32_e32 v244, v244
	v_exp_f32_e32 v245, v245
	s_waitcnt lgkmcnt(1)
	v_mfma_f32_32x32x16_bf16 v[66:81], v[206:209], v[114:117], v[66:81]
	v_add_f32_e32 v250, v250, v230
	v_add_f32_e32 v251, v251, v231
	v_add_f32_e32 v252, v252, v232
	v_add_f32_e32 v253, v253, v233
	v_sub_f32_e32 v246, v246, v197
	v_sub_f32_e32 v247, v247, v197
	v_sub_f32_e32 v248, v248, v197
	v_sub_f32_e32 v249, v249, v197
	v_mfma_f32_32x32x16_bf16 v[82:97], v[202:205], v[118:121], v[82:97]
	v_exp_f32_e32 v246, v246
	v_exp_f32_e32 v247, v247
	v_exp_f32_e32 v248, v248
	v_exp_f32_e32 v249, v249
	v_add_f32_e32 v250, v250, v242
	v_add_f32_e32 v251, v251, v243
	v_add_f32_e32 v252, v252, v244
	v_add_f32_e32 v253, v253, v245
	ds_read_b128 v[198:201], v0 offset:192
	ds_read_b128 v[202:205], v0 offset:224
	ds_read_b128 v[206:209], v0 offset:8896
	ds_read_b128 v[214:217], v0 offset:8928
	s_waitcnt lgkmcnt(4)
	v_mfma_f32_32x32x16_bf16 v[66:81], v[210:213], v[118:121], v[66:81]
	v_add_f32_e32 v250, v250, v246
	v_add_f32_e32 v251, v251, v247
	v_add_f32_e32 v252, v252, v248
	v_add_f32_e32 v253, v253, v249
	v_add_f32_e32 v250, v250, v251
	v_add_f32_e32 v252, v252, v253
	v_add_f32_e32 v250, v250, v252
	v_add_f32_e32 v196, v196, v250
	s_waitcnt lgkmcnt(3)
	v_mfma_f32_32x32x16_bf16 v[82:97], v[198:201], v[122:125], v[82:97]
	v_cvt_pk_bf16_f32 v241, v240, v241
	v_cvt_pk_bf16_f32 v240, v238, v239
	v_cvt_pk_bf16_f32 v239, v236, v237
	v_cvt_pk_bf16_f32 v238, v234, v235
	v_cvt_pk_bf16_f32 v234, v218, v219
	v_cvt_pk_bf16_f32 v235, v220, v221
	v_cvt_pk_bf16_f32 v236, v222, v223
	v_cvt_pk_bf16_f32 v237, v224, v225
	s_waitcnt lgkmcnt(1)
	v_mfma_f32_32x32x16_bf16 v[66:81], v[206:209], v[122:125], v[66:81]
	v_cvt_pk_bf16_f32 v249, v248, v249
	v_cvt_pk_bf16_f32 v248, v246, v247
	v_cvt_pk_bf16_f32 v247, v244, v245
	v_cvt_pk_bf16_f32 v246, v242, v243
	v_cvt_pk_bf16_f32 v242, v226, v227
	v_cvt_pk_bf16_f32 v243, v228, v229
	v_cvt_pk_bf16_f32 v244, v230, v231
	v_cvt_pk_bf16_f32 v245, v232, v233
	v_mfma_f32_32x32x16_bf16 v[82:97], v[202:205], v[126:129], v[82:97]
	s_waitcnt lgkmcnt(0)
	v_mfma_f32_32x32x16_bf16 v[66:81], v[214:217], v[126:129], v[66:81]
	s_add_i32 s76, s77, 63
	s_cmp_le_i32 s76, s27
	s_cbranch_scc1 .Lff2b_z2
	v_cmp_le_i32_e32 vcc, v165, v195
	s_nop 8
	v_cndmask_b32_e32 v66, v155, v66, vcc
	v_cmp_lt_i32_e32 vcc, v163, v195
	s_nop 1
	v_cndmask_b32_e32 v83, v155, v83, vcc
	v_cmp_le_i32_e32 vcc, v163, v195
	s_nop 1
	v_cndmask_b32_e32 v82, v155, v82, vcc
	v_cmp_le_i32_e32 vcc, v166, v195
	s_nop 1
	v_cndmask_b32_e32 v67, v155, v67, vcc
	v_cmp_le_i32_e32 vcc, v167, v195
	s_nop 1
	v_cndmask_b32_e32 v84, v155, v84, vcc
	v_cmp_le_i32_e32 vcc, v168, v195
	s_nop 1
	v_cndmask_b32_e32 v68, v155, v68, vcc
	v_cmp_le_i32_e32 vcc, v169, v195
	s_nop 1
	v_cndmask_b32_e32 v85, v155, v85, vcc
	v_cmp_le_i32_e32 vcc, v170, v195
	s_nop 1
	v_cndmask_b32_e32 v69, v155, v69, vcc
	v_cmp_le_i32_e32 vcc, v171, v195
	s_nop 1
	v_cndmask_b32_e32 v86, v155, v86, vcc
	v_cmp_le_i32_e32 vcc, v172, v195
	s_nop 1
	v_cndmask_b32_e32 v70, v155, v70, vcc
	v_cmp_le_i32_e32 vcc, v173, v195
	s_nop 1
	v_cndmask_b32_e32 v87, v155, v87, vcc
	v_cmp_le_i32_e32 vcc, v174, v195
	s_nop 1
	v_cndmask_b32_e32 v71, v155, v71, vcc
	v_cmp_le_i32_e32 vcc, v175, v195
	s_nop 1
	v_cndmask_b32_e32 v88, v155, v88, vcc
	v_cmp_le_i32_e32 vcc, v176, v195
	s_nop 1
	v_cndmask_b32_e32 v72, v155, v72, vcc
	v_cmp_le_i32_e32 vcc, v177, v195
	s_nop 1
	v_cndmask_b32_e32 v89, v155, v89, vcc
	v_cmp_le_i32_e32 vcc, v178, v195
	s_nop 1
	v_cndmask_b32_e32 v73, v155, v73, vcc
	v_cmp_le_i32_e32 vcc, v179, v195
	s_nop 1
	v_cndmask_b32_e32 v90, v155, v90, vcc
	v_cmp_le_i32_e32 vcc, v180, v195
	s_nop 1
	v_cndmask_b32_e32 v74, v155, v74, vcc
	v_cmp_le_i32_e32 vcc, v181, v195
	s_nop 1
	v_cndmask_b32_e32 v91, v155, v91, vcc
	v_cmp_le_i32_e32 vcc, v182, v195
	s_nop 1
	v_cndmask_b32_e32 v75, v155, v75, vcc
	v_cmp_le_i32_e32 vcc, v183, v195
	s_nop 1
	v_cndmask_b32_e32 v92, v155, v92, vcc
	v_cmp_le_i32_e32 vcc, v184, v195
	s_nop 1
	v_cndmask_b32_e32 v76, v155, v76, vcc
	v_cmp_le_i32_e32 vcc, v185, v195
	s_nop 1
	v_cndmask_b32_e32 v93, v155, v93, vcc
	v_cmp_le_i32_e32 vcc, v186, v195
	s_nop 1
	v_cndmask_b32_e32 v77, v155, v77, vcc
	v_cmp_le_i32_e32 vcc, v187, v195
	s_nop 1
	v_cndmask_b32_e32 v94, v155, v94, vcc
	v_cmp_le_i32_e32 vcc, v188, v195
	s_nop 1
	v_cndmask_b32_e32 v78, v155, v78, vcc
	v_cmp_le_i32_e32 vcc, v189, v195
	s_nop 1
	v_cndmask_b32_e32 v95, v155, v95, vcc
	v_cmp_le_i32_e32 vcc, v190, v195
	s_nop 1
	v_cndmask_b32_e32 v79, v155, v79, vcc
	v_cmp_le_i32_e32 vcc, v191, v195
	s_nop 1
	v_cndmask_b32_e32 v96, v155, v96, vcc
	v_cmp_le_i32_e32 vcc, v192, v195
	s_nop 1
	v_cndmask_b32_e32 v80, v155, v80, vcc
	v_cmp_le_i32_e32 vcc, v193, v195
	s_nop 1
	v_cndmask_b32_e32 v97, v155, v97, vcc
	v_cmp_le_i32_e32 vcc, v194, v195
	s_nop 1
	v_cndmask_b32_e32 v81, v155, v81, vcc

.Lff2b_first:
	s_mul_i32 s20, s7, 0x4400
	v_add_u32_e32 v0, s20, v162
	ds_read_b128 v[198:201], v0
	ds_read_b128 v[202:205], v0 offset:32
	ds_read_b128 v[206:209], v0 offset:8704
	ds_read_b128 v[210:213], v0 offset:8736
	v_add_u32_e32 v78, s75, v161
	v_add_u32_e32 v66, 0x12800, v78
	v_add_u32_e32 v67, 0x12880, v78
	v_add_u32_e32 v70, 0x12820, v78
	v_add_u32_e32 v71, 0x128a0, v78
	v_add_u32_e32 v74, 0x12840, v78
	v_add_u32_e32 v75, 0x128c0, v78
	v_add_u32_e32 v79, 0x12860, v78
	v_add_u32_e32 v78, 0x128e0, v78
	ds_read_b128 v[82:85], v66
	ds_read_b128 v[66:69], v67
	ds_read_b128 v[86:89], v70
	ds_read_b128 v[70:73], v71
	ds_read_b128 v[90:93], v74
	ds_read_b128 v[74:77], v75
	ds_read_b128 v[94:97], v79
	ds_read_b128 v[78:81], v78
	s_waitcnt lgkmcnt(1)
	v_mfma_f32_32x32x16_bf16 v[82:97], v[198:201], v[98:101], v[82:97]
	s_waitcnt lgkmcnt(0)
	v_mfma_f32_32x32x16_bf16 v[66:81], v[206:209], v[98:101], v[66:81]
	v_mfma_f32_32x32x16_bf16 v[82:97], v[202:205], v[102:105], v[82:97]
	ds_read_b128 v[198:201], v0 offset:64
	ds_read_b128 v[202:205], v0 offset:96
	ds_read_b128 v[206:209], v0 offset:8768
	ds_read_b128 v[214:217], v0 offset:8800
	v_mfma_f32_32x32x16_bf16 v[66:81], v[210:213], v[102:105], v[66:81]
	s_waitcnt lgkmcnt(3)
	v_mfma_f32_32x32x16_bf16 v[82:97], v[198:201], v[106:109], v[82:97]
	s_waitcnt lgkmcnt(1)
	v_mfma_f32_32x32x16_bf16 v[66:81], v[206:209], v[106:109], v[66:81]
	v_mfma_f32_32x32x16_bf16 v[82:97], v[202:205], v[110:113], v[82:97]
	ds_read_b128 v[198:201], v0 offset:128
	ds_read_b128 v[202:205], v0 offset:160
	ds_read_b128 v[206:209], v0 offset:8832
	ds_read_b128 v[210:213], v0 offset:8864
	s_waitcnt lgkmcnt(4)
	v_mfma_f32_32x32x16_bf16 v[66:81], v[214:217], v[110:113], v[66:81]
	s_waitcnt lgkmcnt(3)
	v_mfma_f32_32x32x16_bf16 v[82:97], v[198:201], v[114:117], v[82:97]
	s_waitcnt lgkmcnt(1)
	v_mfma_f32_32x32x16_bf16 v[66:81], v[206:209], v[114:117], v[66:81]
	v_mfma_f32_32x32x16_bf16 v[82:97], v[202:205], v[118:121], v[82:97]
	ds_read_b128 v[198:201], v0 offset:192
	ds_read_b128 v[202:205], v0 offset:224
	ds_read_b128 v[206:209], v0 offset:8896
	ds_read_b128 v[214:217], v0 offset:8928
	s_waitcnt lgkmcnt(4)
	v_mfma_f32_32x32x16_bf16 v[66:81], v[210:213], v[118:121], v[66:81]
	s_waitcnt lgkmcnt(3)
	v_mfma_f32_32x32x16_bf16 v[82:97], v[198:201], v[122:125], v[82:97]
	s_waitcnt lgkmcnt(1)
	v_mfma_f32_32x32x16_bf16 v[66:81], v[206:209], v[122:125], v[66:81]
	v_mfma_f32_32x32x16_bf16 v[82:97], v[202:205], v[126:129], v[82:97]
	s_waitcnt lgkmcnt(0)
	v_mfma_f32_32x32x16_bf16 v[66:81], v[214:217], v[126:129], v[66:81]
	s_add_i32 s76, s77, 63
	s_cmp_le_i32 s76, s27
	s_cbranch_scc1 .Lff2b_m1
	v_cmp_le_i32_e32 vcc, v165, v195
	s_nop 8
	v_cndmask_b32_e32 v66, v155, v66, vcc
	v_cmp_lt_i32_e32 vcc, v163, v195
	s_nop 1
	v_cndmask_b32_e32 v83, v155, v83, vcc
	v_cmp_le_i32_e32 vcc, v163, v195
	s_nop 1
	v_cndmask_b32_e32 v82, v155, v82, vcc
	v_cmp_le_i32_e32 vcc, v166, v195
	s_nop 1
	v_cndmask_b32_e32 v67, v155, v67, vcc
	v_cmp_le_i32_e32 vcc, v167, v195
	s_nop 1
	v_cndmask_b32_e32 v84, v155, v84, vcc
	v_cmp_le_i32_e32 vcc, v168, v195
	s_nop 1
	v_cndmask_b32_e32 v68, v155, v68, vcc
	v_cmp_le_i32_e32 vcc, v169, v195
	s_nop 1
	v_cndmask_b32_e32 v85, v155, v85, vcc
	v_cmp_le_i32_e32 vcc, v170, v195
	s_nop 1
	v_cndmask_b32_e32 v69, v155, v69, vcc
	v_cmp_le_i32_e32 vcc, v171, v195
	s_nop 1
	v_cndmask_b32_e32 v86, v155, v86, vcc
	v_cmp_le_i32_e32 vcc, v172, v195
	s_nop 1
	v_cndmask_b32_e32 v70, v155, v70, vcc
	v_cmp_le_i32_e32 vcc, v173, v195
	s_nop 1
	v_cndmask_b32_e32 v87, v155, v87, vcc
	v_cmp_le_i32_e32 vcc, v174, v195
	s_nop 1
	v_cndmask_b32_e32 v71, v155, v71, vcc
	v_cmp_le_i32_e32 vcc, v175, v195
	s_nop 1
	v_cndmask_b32_e32 v88, v155, v88, vcc
	v_cmp_le_i32_e32 vcc, v176, v195
	s_nop 1
	v_cndmask_b32_e32 v72, v155, v72, vcc
	v_cmp_le_i32_e32 vcc, v177, v195
	s_nop 1
	v_cndmask_b32_e32 v89, v155, v89, vcc
	v_cmp_le_i32_e32 vcc, v178, v195
	s_nop 1
	v_cndmask_b32_e32 v73, v155, v73, vcc
	v_cmp_le_i32_e32 vcc, v179, v195
	s_nop 1
	v_cndmask_b32_e32 v90, v155, v90, vcc
	v_cmp_le_i32_e32 vcc, v180, v195
	s_nop 1
	v_cndmask_b32_e32 v74, v155, v74, vcc
	v_cmp_le_i32_e32 vcc, v181, v195
	s_nop 1
	v_cndmask_b32_e32 v91, v155, v91, vcc
	v_cmp_le_i32_e32 vcc, v182, v195
	s_nop 1
	v_cndmask_b32_e32 v75, v155, v75, vcc
	v_cmp_le_i32_e32 vcc, v183, v195
	s_nop 1
	v_cndmask_b32_e32 v92, v155, v92, vcc
	v_cmp_le_i32_e32 vcc, v184, v195
	s_nop 1
	v_cndmask_b32_e32 v76, v155, v76, vcc
	v_cmp_le_i32_e32 vcc, v185, v195
	s_nop 1
	v_cndmask_b32_e32 v93, v155, v93, vcc
	v_cmp_le_i32_e32 vcc, v186, v195
	s_nop 1
	v_cndmask_b32_e32 v77, v155, v77, vcc
	v_cmp_le_i32_e32 vcc, v187, v195
	s_nop 1
	v_cndmask_b32_e32 v94, v155, v94, vcc
	v_cmp_le_i32_e32 vcc, v188, v195
	s_nop 1
	v_cndmask_b32_e32 v78, v155, v78, vcc
	v_cmp_le_i32_e32 vcc, v189, v195
	s_nop 1
	v_cndmask_b32_e32 v95, v155, v95, vcc
	v_cmp_le_i32_e32 vcc, v190, v195
	s_nop 1
	v_cndmask_b32_e32 v79, v155, v79, vcc
	v_cmp_le_i32_e32 vcc, v191, v195
	s_nop 1
	v_cndmask_b32_e32 v96, v155, v96, vcc
	v_cmp_le_i32_e32 vcc, v192, v195
	s_nop 1
	v_cndmask_b32_e32 v80, v155, v80, vcc
	v_cmp_le_i32_e32 vcc, v193, v195
	s_nop 1
	v_cndmask_b32_e32 v97, v155, v97, vcc
	v_cmp_le_i32_e32 vcc, v194, v195
	s_nop 1
	v_cndmask_b32_e32 v81, v155, v81, vcc
